# v028
# speedup vs baseline: 1.0188x; 1.0047x over previous
; __device__ __forceinline__ int otid(int wvs) { int l; asm volatile("v_mbcnt_lo_u32_b32 %0, -1, 0\n\tv_mbcnt_hi_u32_b32 %0, -1, %0" : "=v"(l)); return wvs * 64 + l; }
; __device__ __forceinline__ int v_rd_base(int lane) { return ((lane & 3) << 3) | (((lane >> 2) & 3) << 6) | (((lane >> 4) & 1) << 5) | (((lane >> 5) & 1) << 8); }
; #define ISSUE_K(t, slot) do { const char* kg_ = (const char*)(Kh + (long)(t) * (KVBLK * 192)); char* kl_ = K_lds + (slot) * SHM_K + tid * 16; \
;     DMA16(kg_ + kso0, kl_); DMA16(kg_ + kso1, kl_ + 8192); DMA16(kg_ + kso2, kl_ + 16384); } while (0)
; __device__ __forceinline__ void attn_body(const u16* __restrict__ Qb, const u16* __restrict__ Kh, const u16* __restrict__ Vh,
;                                           u16* __restrict__ Ob, int seq, int wvs) {
;     ...
;   const int tid = otid(wvs), wid = tid >> 6, lane = tid & 63, r32 = lane & 31, hi = lane >> 5;
;   char* V_lds = lds; char* K_lds = lds + 3 * SHM_V;
;   float* ws = (float*)(lds + 3 * SHM_V + 3 * SHM_K) + wid * 64; float* li_l = ws; float* al_l = ws + 32;
;   float m_reg = -1e30f, l_reg = 0; f32x16 o[4] = {}; bf16x8 qr[12];
;   const u16* Qw = Qb + (long)(wid * QBLK + r32) * 192 + hi * 8;
; #pragma unroll
;   for (int d0 = 0; d0 < 12; ++d0) qr[d0] = *reinterpret_cast<const bf16x8*>(Qw + d0 * 16);
;   unsigned kso0, kso1, kso2, vso0, vso1;
;   { int p = tid * 16, row = p / 384, pc = p - row * 384; kso0 = row * 384 + (pc ^ (((row >> 1) & 7) << 4));
;     p = 8192 + tid * 16; row = p / 384; pc = p - row * 384; kso1 = row * 384 + (pc ^ (((row >> 1) & 7) << 4));
;     p = 16384 + tid * 16; row = p / 384; pc = p - row * 384; kso2 = row * 384 + (pc ^ (((row >> 1) & 7) << 4)); }
;   { int p = tid * 16, sub = p >> 9, w = p & 511, kk = (sub >> 2) * 8 + (w >> 6), c = (sub & 3) * 32 + ((w & 63) >> 1);
;     int k = (kk & ~0xC) | ((kk & 4) << 1) | ((kk & 8) >> 1); vso0 = k * 256 + c * 2;
;     p = 8192 + tid * 16; sub = p >> 9; w = p & 511; kk = (sub >> 2) * 8 + (w >> 6); c = (sub & 3) * 32 + ((w & 63) >> 1);
;     k = (kk & ~0xC) | ((kk & 4) << 1) | ((kk & 8) >> 1); vso1 = k * 256 + c * 2; }
;   const int vb0 = (int)(uintptr_t)V_lds + v_rd_base(lane);
;     ...
;   f32x16 pA0, pA1, pB0, pB1; float mnA, mnB, alA, alB; bf16x8 pa0, pa1, pa2, pa3; const int NT = seq / KVBLK;
;   ISSUE_K(0, 0); ISSUE_V(0, 0); ISSUE_K(1, 1);
;   TBAR(5);
.LBB0_329:
	s_and_b64 vcc, exec, s[10:11]
	s_cbranch_vccz .LBB0_767
	v_mbcnt_lo_u32_b32 v2, -1, 0
	v_mbcnt_hi_u32_b32 v2, -1, v2
	s_movk_i32 s4, 0xffe0
	v_add_u32_e32 v3, s69, v2
	v_ashrrev_i32_e32 v4, 1, v3
	v_bfi_b32 v5, s4, v4, v2
	v_readlane_b32 s4, v255, 0
	v_readlane_b32 s5, v255, 1
	v_bfe_u32 v186, v2, 5, 1
	v_lshlrev_b32_e32 v160, 4, v186
	v_mov_b64_e32 v[0:1], s[4:5]
	v_mad_i64_i32 v[0:1], s[4:5], v5, s56, v[0:1]
	v_lshl_add_u64 v[0:1], v[0:1], 0, v[160:161]
	s_mov_b32 s4, 0x2aaaaaab
	flat_load_dwordx4 v[140:143], v[0:1]
	flat_load_dwordx4 v[136:139], v[0:1] offset:32
	flat_load_dwordx4 v[132:135], v[0:1] offset:64
	flat_load_dwordx4 v[128:131], v[0:1] offset:96
	flat_load_dwordx4 v[124:127], v[0:1] offset:128
	flat_load_dwordx4 v[120:123], v[0:1] offset:160
	flat_load_dwordx4 v[116:119], v[0:1] offset:192
	flat_load_dwordx4 v[112:115], v[0:1] offset:224
	flat_load_dwordx4 v[108:111], v[0:1] offset:256
	flat_load_dwordx4 v[104:107], v[0:1] offset:288
	flat_load_dwordx4 v[100:103], v[0:1] offset:320
	flat_load_dwordx4 v[96:99], v[0:1] offset:352
	v_mul_hi_i32 v1, v3, s4
	v_lshrrev_b32_e32 v5, 31, v1
	v_ashrrev_i32_e32 v1, 2, v1
	v_add_u32_e32 v1, v1, v5
	v_lshlrev_b32_e32 v0, 4, v3
	v_mul_lo_u32 v5, v1, s56
	v_lshlrev_b32_e32 v1, 3, v1
	v_sub_u32_e32 v6, v0, v5
	v_and_b32_e32 v1, 0x70, v1
	v_xad_u32 v48, v6, v1, v5
	v_add_u32_e32 v1, 0x2000, v0
	v_mul_hi_i32 v5, v1, s4
	v_lshrrev_b32_e32 v6, 31, v5
	v_ashrrev_i32_e32 v5, 6, v5
	v_add_u32_e32 v5, v5, v6
	v_mul_i32_i24_e32 v6, 0x180, v5
	v_lshlrev_b32_e32 v5, 3, v5
	v_sub_u32_e32 v7, v1, v6
	v_and_b32_e32 v5, 0x70, v5
	v_xad_u32 v50, v7, v5, v6
	v_add_u32_e32 v5, 0x4000, v0
	v_mul_hi_i32 v6, v5, s4
	v_lshrrev_b32_e32 v7, 31, v6
	v_ashrrev_i32_e32 v6, 6, v6
	v_add_u32_e32 v6, v6, v7
	v_mul_i32_i24_e32 v7, 0x180, v6
	v_lshlrev_b32_e32 v6, 3, v6
	v_sub_u32_e32 v5, v5, v7
	v_and_b32_e32 v6, 0x70, v6
	v_xad_u32 v52, v5, v6, v7
	v_ashrrev_i32_e32 v5, 4, v3
	v_ashrrev_i32_e32 v1, 8, v1
	v_and_b32_e32 v63, -16, v5
	v_lshrrev_b32_e32 v6, 1, v3
	v_lshrrev_b32_e32 v5, 1, v5
	v_lshrrev_b32_e32 v7, 1, v1
	v_and_b32_e32 v64, 8, v6
	v_and_b32_e32 v65, 4, v5
	v_lshlrev_b32_e32 v6, 1, v3
	v_and_b32_e32 v7, 4, v7
	v_bfe_u32 v62, v3, 2, 2
	v_or_b32_e32 v5, v65, v63
	v_and_b32_e32 v66, 0xc0, v6
	v_and_b32_e32 v67, 48, v0
	v_and_or_b32 v68, v1, -16, v7
	v_or3_b32 v5, v5, v62, v64
	v_or_b32_e32 v6, v67, v66
	v_or3_b32 v1, v68, v62, v64
	v_add_u32_e32 v192, 0, v0
	v_lshl_or_b32 v5, v5, 8, v6
	v_bfe_u32 v252, v5, 10, 1
	v_bfe_u32 v253, v5, 11, 1
	v_xor_b32_e32 v252, v252, v253
	v_mul_u32_u24_e32 v252, 0xc00, v252
	v_xor_b32_e32 v5, v5, v252
	v_lshl_or_b32 v1, v1, 8, v6
	v_bfe_u32 v252, v1, 10, 1
	v_bfe_u32 v253, v1, 11, 1
	v_xor_b32_e32 v252, v252, v253
	v_mul_u32_u24_e32 v252, 0xc00, v252
	v_xor_b32_e32 v1, v1, v252
	v_add_u32_e32 v6, 0xc000, v192
	s_add_i32 s6, 0, 0x1e000
	v_readfirstlane_b32 s5, v6
	v_add_u32_e32 v6, 0xe000, v192
	s_mov_b32 m0, s5
	v_readfirstlane_b32 s5, v6
	v_add_u32_e32 v6, 0x10000, v192
	global_load_lds_dwordx4 v48, s[86:87]
	s_mov_b32 m0, s5
	v_readfirstlane_b32 s5, v6
	global_load_lds_dwordx4 v50, s[86:87]
	s_mov_b32 m0, s5
	v_readfirstlane_b32 s5, v192
	v_add_u32_e32 v6, 0x2000, v192
	s_cmp_lg_u32 0, -1
	global_load_lds_dwordx4 v52, s[86:87]
	s_mov_b32 m0, s5
	v_readfirstlane_b32 s5, v6
	s_cselect_b32 s4, 0, 0
	global_load_lds_dwordx4 v5, s[28:29]
	s_mov_b32 m0, s5
	s_add_i32 s5, 0, 0x12000
	v_add_u32_e32 v6, s5, v0
	v_add_u32_e32 v7, 0x2000, v6
	v_readfirstlane_b32 s5, v6
	global_load_lds_dwordx4 v1, s[28:29]
	s_mov_b32 m0, s5
	v_readfirstlane_b32 s5, v7
	v_add_u32_e32 v6, 0x4000, v6
	global_load_lds_dwordx4 v48, s[54:55]
	s_mov_b32 m0, s5
	v_readfirstlane_b32 s5, v6
	global_load_lds_dwordx4 v50, s[54:55]
	s_mov_b32 m0, s5
	v_and_b32_e32 v69, 63, v2
	global_load_lds_dwordx4 v52, s[54:55]
	v_and_b32_e32 v3, 0x3fffffc0, v3
	v_and_b32_e32 v164, 0xffffffe0, v4
	v_lshlrev_b32_e32 v4, 4, v2
	v_lshl_add_u32 v165, v3, 2, s6
	v_lshlrev_b32_e32 v3, 3, v69
	v_and_b32_e32 v4, 0xc0, v4
	v_lshlrev_b32_e32 v6, 1, v2
	v_and_or_b32 v4, v3, 24, v4
	v_and_b32_e32 v6, 32, v6
	v_and_b32_e32 v3, 0x100, v3
	s_waitcnt vmcnt(5) lgkmcnt(0)
	v_or3_b32 v3, v4, v6, v3
	v_and_b32_e32 v187, 31, v2
	s_mov_b32 s31, 1
	s_mov_b32 s30, 4
	s_mov_b32 s12, 0
	v_add_u32_e32 v190, s4, v3
	v_mov_b32_e32 v49, v161
	v_mov_b32_e32 v51, v161
	v_mov_b32_e32 v53, v161
	s_barrier
; #define ISSUE_K(t, slot) do { const char* kg_ = (const char*)(Kh + (long)(t) * (KVBLK * 192)); char* kl_ = K_lds + (slot) * SHM_K + tid * 16; \
;     DMA16(kg_ + kso0, kl_); DMA16(kg_ + kso1, kl_ + 8192); DMA16(kg_ + kso2, kl_ + 16384); } while (0)
; #define ISSUE_V(t, slot) do { const char* vg_ = (const char*)(Vh + (long)(t) * (KVBLK * 128)); char* vl_ = V_lds + (slot) * SHM_V + tid * 16; \
;     DMA16(vg_ + vso0, vl_); DMA16(vg_ + vso1, vl_ + 8192); } while (0)
; __device__ __forceinline__ void qkt(f32x16& p0, f32x16& p1, const char* Ks, const bf16x8* qr, int r32, int hi) {
;   p0 = f32x16{}; p1 = f32x16{};
; #pragma unroll
;   for (int d0 = 0; d0 < 12; ++d0) { int cb = (d0 * 16 + hi * 8) * 2;
;     bf16x8 b0 = *reinterpret_cast<const bf16x8*>(Ks + KSWZ(r32, cb));
;     bf16x8 b1 = *reinterpret_cast<const bf16x8*>(Ks + KSWZ(32 + r32, cb));
;     p0 = __builtin_amdgcn_mfma_f32_32x32x16_bf16(b0, qr[d0], p0, 0, 0, 0);
;     p1 = __builtin_amdgcn_mfma_f32_32x32x16_bf16(b1, qr[d0], p1, 0, 0, 0); }
; }
; __device__ __forceinline__ void attn_body(const u16* __restrict__ Qb, const u16* __restrict__ Kh, const u16* __restrict__ Vh,
;                                           u16* __restrict__ Ob, int seq, int wvs) {
;     ...
;   ISSUE_K(2, 2); ISSUE_V(1, 1);
;   qkt(pA0, pA1, K_lds, qr, r32, hi); partialSM(pA0, pA1, m_reg, mnA, alA);
	v_add_u32_e32 v0, s83, v0
	v_add_u32_e32 v3, 0x2000, v0
	v_readfirstlane_b32 s4, v0
	s_mov_b32 m0, s4
	v_readfirstlane_b32 s4, v3
	v_add_u32_e32 v0, 0x4000, v0
	global_load_lds_dwordx4 v48, s[44:45]
	s_mov_b32 m0, s4
	v_readfirstlane_b32 s4, v0
	v_add_u32_e32 v0, 0x4000, v192
	global_load_lds_dwordx4 v50, s[44:45]
	s_mov_b32 m0, s4
	v_readfirstlane_b32 s4, v0
	v_add_u32_e32 v0, 0x6000, v192
	global_load_lds_dwordx4 v52, s[44:45]
	s_mov_b32 m0, s4
	v_readfirstlane_b32 s4, v0
	v_lshlrev_b32_e32 v0, 3, v2
	v_mul_u32_u24_e32 v8, 0x180, v187
	v_and_b32_e32 v9, 0x70, v0
	global_load_lds_dwordx4 v5, s[50:51]
	s_mov_b32 m0, s4
	v_bitop3_b32 v193, v160, v8, v9 bitop3:0xde
	global_load_lds_dwordx4 v1, s[50:51]
	v_add_u32_e32 v4, 0, v193
	ds_read_b128 v[0:3], v4 offset:49152
	ds_read_b128 v[4:7], v4 offset:61440
	s_waitcnt vmcnt(0) lgkmcnt(0)
	v_mfma_f32_32x32x16_bf16 v[16:31], v[0:3], v[140:143], 0
	v_or_b32_e32 v0, 32, v160
	v_bitop3_b32 v199, v0, v8, v9 bitop3:0xde
	s_mov_b32 s13, s12
	s_mov_b32 s14, s12
	s_mov_b32 s15, s12
	s_mov_b32 s16, s12
	s_mov_b32 s17, s12
	v_mfma_f32_32x32x16_bf16 v[32:47], v[4:7], v[140:143], 0
	v_add_u32_e32 v4, 0, v199
	ds_read_b128 v[0:3], v4 offset:49152
	ds_read_b128 v[4:7], v4 offset:61440
	s_mov_b32 s18, s12
	s_mov_b32 s19, s12
	s_mov_b32 s20, s12
	s_mov_b32 s21, s12
	s_mov_b32 s22, s12
	s_waitcnt lgkmcnt(1)
	v_mfma_f32_32x32x16_bf16 v[16:31], v[0:3], v[136:139], v[16:31]
	v_or_b32_e32 v0, 64, v160
	v_bitop3_b32 v200, v0, v8, v9 bitop3:0xde
	s_mov_b32 s23, s12
	s_mov_b32 s24, s12
	s_mov_b32 s25, s12
	s_mov_b32 s26, s12
	s_mov_b32 s27, s12
	s_waitcnt lgkmcnt(0)
	v_mfma_f32_32x32x16_bf16 v[32:47], v[4:7], v[136:139], v[32:47]
	v_add_u32_e32 v4, 0, v200
	ds_read_b128 v[0:3], v4 offset:49152
	ds_read_b128 v[4:7], v4 offset:61440
	v_mov_b32_e32 v168, v52
	v_mov_b32_e32 v167, v50
	v_mov_b32_e32 v166, v48
	s_add_u32 s98, s80, s48
	s_addc_u32 s99, s81, s49
	s_add_u32 s98, s98, s70
	s_addc_u32 s99, s99, s71
	v_cmp_gt_u32_e64 s[6:7], 32, v69
	v_lshl_add_u32 v188, v187, 2, v165
	s_waitcnt lgkmcnt(1)
	v_mfma_f32_32x32x16_bf16 v[16:31], v[0:3], v[132:135], v[16:31]
	v_or_b32_e32 v0, 0x60, v160
	v_bitop3_b32 v202, v0, v8, v9 bitop3:0xde
	v_mov_b32_e32 v189, 0
	s_waitcnt lgkmcnt(0)
	v_mfma_f32_32x32x16_bf16 v[32:47], v[4:7], v[132:135], v[32:47]
	v_add_u32_e32 v4, 0, v202
	ds_read_b128 v[0:3], v4 offset:49152
	ds_read_b128 v[4:7], v4 offset:61440
	s_waitcnt lgkmcnt(1)
	v_mfma_f32_32x32x16_bf16 v[16:31], v[0:3], v[128:131], v[16:31]
	v_or_b32_e32 v0, 0x80, v160
	v_xad_u32 v207, v0, v9, v8
	v_add_u32_e32 v10, 0, v207
	s_waitcnt lgkmcnt(0)
	v_mfma_f32_32x32x16_bf16 v[32:47], v[4:7], v[128:131], v[32:47]
	ds_read_b128 v[0:3], v10 offset:49152
	ds_read_b128 v[4:7], v10 offset:61440
	s_waitcnt lgkmcnt(1)
	v_mfma_f32_32x32x16_bf16 v[16:31], v[0:3], v[124:127], v[16:31]
	v_or_b32_e32 v0, 0xa0, v160
	v_xad_u32 v203, v0, v9, v8
	v_add_u32_e32 v10, 0, v203
	s_waitcnt lgkmcnt(0)
	v_mfma_f32_32x32x16_bf16 v[32:47], v[4:7], v[124:127], v[32:47]
	ds_read_b128 v[0:3], v10 offset:49152
	ds_read_b128 v[4:7], v10 offset:61440
	s_waitcnt lgkmcnt(1)
	v_mfma_f32_32x32x16_bf16 v[16:31], v[0:3], v[120:123], v[16:31]
	v_or_b32_e32 v0, 0xc0, v160
	v_xad_u32 v201, v0, v9, v8
	v_add_u32_e32 v10, 0, v201
	s_waitcnt lgkmcnt(0)
	v_mfma_f32_32x32x16_bf16 v[32:47], v[4:7], v[120:123], v[32:47]
	ds_read_b128 v[0:3], v10 offset:49152
	ds_read_b128 v[4:7], v10 offset:61440
	s_waitcnt lgkmcnt(1)
	v_mfma_f32_32x32x16_bf16 v[16:31], v[0:3], v[116:119], v[16:31]
	v_or_b32_e32 v0, 0xe0, v160
	v_xad_u32 v198, v0, v9, v8
	v_add_u32_e32 v10, 0, v198
	s_waitcnt lgkmcnt(0)
	v_mfma_f32_32x32x16_bf16 v[32:47], v[4:7], v[116:119], v[32:47]
	ds_read_b128 v[0:3], v10 offset:49152
	ds_read_b128 v[4:7], v10 offset:61440
	s_waitcnt lgkmcnt(1)
	v_mfma_f32_32x32x16_bf16 v[16:31], v[0:3], v[112:115], v[16:31]
	v_or_b32_e32 v0, 0x100, v160
	v_xad_u32 v197, v0, v9, v8
	v_add_u32_e32 v10, 0, v197
	s_waitcnt lgkmcnt(0)
	v_mfma_f32_32x32x16_bf16 v[32:47], v[4:7], v[112:115], v[32:47]
	ds_read_b128 v[0:3], v10 offset:49152
	ds_read_b128 v[4:7], v10 offset:61440
	s_waitcnt lgkmcnt(1)
	v_mfma_f32_32x32x16_bf16 v[16:31], v[0:3], v[108:111], v[16:31]
	v_or_b32_e32 v0, 0x120, v160
	v_xad_u32 v196, v0, v9, v8
	v_add_u32_e32 v10, 0, v196
	ds_read_b128 v[0:3], v10 offset:49152
	s_waitcnt lgkmcnt(1)
	v_mfma_f32_32x32x16_bf16 v[32:47], v[4:7], v[108:111], v[32:47]
	ds_read_b128 v[4:7], v10 offset:61440
	s_waitcnt lgkmcnt(1)
	v_mfma_f32_32x32x16_bf16 v[16:31], v[0:3], v[104:107], v[16:31]
	v_or_b32_e32 v0, 0x140, v160
	v_xad_u32 v195, v0, v9, v8
	v_add_u32_e32 v10, 0, v195
	ds_read_b128 v[0:3], v10 offset:49152
	ds_read_b128 v[54:57], v10 offset:61440
	s_waitcnt lgkmcnt(2)
	v_mfma_f32_32x32x16_bf16 v[32:47], v[4:7], v[104:107], v[32:47]
	v_or_b32_e32 v4, 0x160, v160
	v_xad_u32 v194, v4, v9, v8
	v_add_u32_e32 v8, 0, v194
	ds_read_b128 v[4:7], v8 offset:49152
	ds_read_b128 v[58:61], v8 offset:61440
	s_waitcnt lgkmcnt(3)
	v_mfma_f32_32x32x16_bf16 v[16:31], v[0:3], v[100:103], v[16:31]
	s_waitcnt lgkmcnt(1)
	v_mfma_f32_32x32x16_bf16 v[16:31], v[4:7], v[96:99], v[16:31]
	v_mov_b64_e32 v[0:1], s[12:13]
	v_mov_b64_e32 v[14:15], s[26:27]
	v_mov_b64_e32 v[2:3], s[14:15]
	v_mov_b64_e32 v[4:5], s[16:17]
	v_mov_b64_e32 v[6:7], s[18:19]
	v_mov_b64_e32 v[8:9], s[20:21]
	v_mov_b64_e32 v[10:11], s[22:23]
	v_mfma_f32_32x32x16_bf16 v[32:47], v[54:57], v[100:103], v[32:47]
	s_nop 3
	v_max_f32_e32 v70, v17, v17
	v_max_f32_e32 v71, v16, v16
	v_max_f32_e32 v70, v71, v70
	v_max3_f32 v54, v70, v18, v19
	v_max3_f32 v54, v54, v20, v21
	v_max3_f32 v54, v54, v22, v23
	v_max3_f32 v54, v54, v24, v25
	s_waitcnt lgkmcnt(0)
; #define ISSUE_K(t, slot) do { const char* kg_ = (const char*)(Kh + (long)(t) * (KVBLK * 192)); char* kl_ = K_lds + (slot) * SHM_K + tid * 16; \
;     DMA16(kg_ + kso0, kl_); DMA16(kg_ + kso1, kl_ + 8192); DMA16(kg_ + kso2, kl_ + 16384); } while (0)
; #define ISSUE_V(t, slot) do { const char* vg_ = (const char*)(Vh + (long)(t) * (KVBLK * 128)); char* vl_ = V_lds + (slot) * SHM_V + tid * 16; \
;     DMA16(vg_ + vso0, vl_); DMA16(vg_ + vso1, vl_ + 8192); } while (0)
; #define TBAR(n) do { asm volatile("s_waitcnt vmcnt(" #n ") lgkmcnt(0)" ::: "memory"); __builtin_amdgcn_s_barrier(); SBAR(); } while (0)
; __device__ __forceinline__ void partialSM(f32x16& p0, f32x16& p1, float& m_reg, float& mn, float& alpha) {
;   constexpr float C = ASCALE * 1.4426950408889634f;
;   float pmax = p0[0]; for (int r = 1; r < 16; ++r) pmax = fmaxf(pmax, p0[r]); for (int r = 0; r < 16; ++r) pmax = fmaxf(pmax, p1[r]);
;   { auto rr = __builtin_amdgcn_permlane32_swap(__float_as_uint(pmax), __float_as_uint(pmax), false, false);
;     pmax = fmaxf(__uint_as_float(rr[0]), __uint_as_float(rr[1])); }
;   if (__builtin_expect(__all(pmax - m_reg <= THR / ASCALE), 1)) { mn = m_reg; alpha = 1.f; }
;   else { mn = fmaxf(m_reg, pmax); alpha = __builtin_amdgcn_exp2f((m_reg - mn) * C); m_reg = mn; }
;   float mnC = -mn * C;
;   for (int r = 0; r < 16; ++r) p0[r] = fmaf(p0[r], C, mnC); for (int r = 0; r < 16; ++r) p1[r] = fmaf(p1[r], C, mnC);
;   for (int r = 0; r < 16; ++r) p0[r] = __builtin_amdgcn_exp2f(p0[r]);
; __device__ __forceinline__ void attn_body(const u16* __restrict__ Qb, const u16* __restrict__ Kh, const u16* __restrict__ Vh,
;                                           u16* __restrict__ Ob, int seq, int wvs) {
;     ...
;   for (int j = 1; j + 1 < NT; j += 2) {
;     TBAR(5);
;     ISSUE_K(j + 2, NEXT3(NEXT3(sK))); ISSUE_V(j + 1, NEXT3(NEXT3(sV)));
;     qkt(pB0, pB1, K_lds + sK * SHM_K, qr, r32, hi);
	v_mfma_f32_32x32x16_bf16 v[32:47], v[58:61], v[96:99], v[32:47]
	v_max3_f32 v54, v54, v26, v27
	v_max3_f32 v54, v54, v28, v29
	v_max3_f32 v54, v54, v30, v31
	v_mov_b64_e32 v[12:13], s[24:25]
	s_nop 7
	v_max3_f32 v54, v54, v32, v33
	v_max3_f32 v54, v54, v34, v35
	v_max3_f32 v54, v54, v36, v37
	v_max3_f32 v54, v54, v38, v39
	v_max3_f32 v54, v54, v40, v41
	v_max3_f32 v54, v54, v42, v43
	v_max3_f32 v54, v54, v44, v45
	v_max3_f32 v54, v54, v46, v47
	v_mov_b32_e32 v55, v54
	s_nop 1
	v_permlane32_swap_b32_e32 v54, v55
	v_max_f32_e32 v55, v55, v55
	v_max_f32_e32 v54, v54, v54
	v_max_f32_e32 v54, v54, v55
	v_add_f32_e32 v55, 0x7149f2ca, v54
	v_cmp_ge_f32_e32 vcc, s35, v55
	s_cmp_eq_u64 vcc, exec
	v_max_f32_e32 v54, 0xf149f2ca, v54
	s_cselect_b64 vcc, -1, 0
	v_mov_b32_e32 v55, 0xf149f2ca
	v_cndmask_b32_e32 v191, v54, v55, vcc
	v_sub_f32_e32 v56, 0xf149f2ca, v54
	v_mul_f32_e32 v54, 0xbdd53b94, v191
	v_fmamk_f32 v16, v16, 0x3dd53b94, v54
	v_exp_f32_e32 v218, v16
	v_fmamk_f32 v16, v17, 0x3dd53b94, v54
	v_exp_f32_e32 v220, v16
	v_fmamk_f32 v16, v18, 0x3dd53b94, v54
	v_exp_f32_e32 v221, v16
	v_fmamk_f32 v16, v19, 0x3dd53b94, v54
	v_exp_f32_e32 v222, v16
	v_fmamk_f32 v16, v20, 0x3dd53b94, v54
	v_exp_f32_e32 v223, v16
	v_fmamk_f32 v16, v21, 0x3dd53b94, v54
	v_exp_f32_e32 v225, v16
	v_fmamk_f32 v16, v22, 0x3dd53b94, v54
	v_exp_f32_e32 v224, v16
	v_fmamk_f32 v16, v23, 0x3dd53b94, v54
	v_exp_f32_e32 v226, v16
	v_fmamk_f32 v16, v24, 0x3dd53b94, v54
	v_exp_f32_e32 v211, v16
	v_fmamk_f32 v16, v25, 0x3dd53b94, v54
	v_exp_f32_e32 v212, v16
	v_fmamk_f32 v16, v26, 0x3dd53b94, v54
	v_exp_f32_e32 v213, v16
	v_fmamk_f32 v16, v27, 0x3dd53b94, v54
	v_exp_f32_e32 v215, v16
	v_fmamk_f32 v16, v28, 0x3dd53b94, v54
	v_exp_f32_e32 v214, v16
	v_fmamk_f32 v16, v29, 0x3dd53b94, v54
	v_exp_f32_e32 v216, v16
	v_fmamk_f32 v16, v30, 0x3dd53b94, v54
	v_exp_f32_e32 v217, v16
	v_or3_b32 v16, v68, v64, v62
	v_lshlrev_b32_e32 v16, 8, v16
	v_mul_f32_e32 v56, 0x3dd53b94, v56
	v_or3_b32 v16, v16, v66, v67
	v_mov_b32_e32 v17, v161
	v_exp_f32_e32 v56, v56
	v_bfe_u32 v252, v16, 10, 1
	v_bfe_u32 v253, v16, 11, 1
	v_xor_b32_e32 v252, v252, v253
	v_mul_u32_u24_e32 v252, 0xc00, v252
	v_xor_b32_e32 v16, v16, v252
	v_mov_b32_e32 v170, v16
	s_add_u32 s100, s80, s88
	s_addc_u32 s101, s81, s89
	s_add_u32 s100, s100, s72
	s_addc_u32 s101, s101, s73
	v_or_b32_e32 v16, v63, v64
	v_pk_fma_f32 v[144:145], v[46:47], s[68:69], v[54:55] op_sel_hi:[1,0,0]
	v_pk_fma_f32 v[146:147], v[44:45], s[68:69], v[54:55] op_sel_hi:[1,0,0]
	v_pk_fma_f32 v[148:149], v[42:43], s[68:69], v[54:55] op_sel_hi:[1,0,0]
	v_pk_fma_f32 v[150:151], v[40:41], s[68:69], v[54:55] op_sel_hi:[1,0,0]
	v_pk_fma_f32 v[152:153], v[38:39], s[68:69], v[54:55] op_sel_hi:[1,0,0]
	v_pk_fma_f32 v[154:155], v[36:37], s[68:69], v[54:55] op_sel_hi:[1,0,0]
	v_pk_fma_f32 v[156:157], v[34:35], s[68:69], v[54:55] op_sel_hi:[1,0,0]
	v_pk_fma_f32 v[158:159], v[32:33], s[68:69], v[54:55] op_sel_hi:[1,0,0]
	v_fmac_f32_e32 v54, 0x3dd53b94, v31
	v_or3_b32 v16, v16, v65, v62
	v_exp_f32_e32 v219, v54
	v_lshlrev_b32_e32 v16, 8, v16
	v_or3_b32 v16, v16, v66, v67
	v_cndmask_b32_e64 v208, v56, 1.0, vcc
	v_bfe_u32 v252, v16, 10, 1
	v_bfe_u32 v253, v16, 11, 1
	v_xor_b32_e32 v252, v252, v253
	v_mul_u32_u24_e32 v252, 0xc00, v252
	v_xor_b32_e32 v16, v16, v252
	v_mov_b32_e32 v169, v16
	v_mov_b64_e32 v[62:63], v[14:15]
	v_mov_b64_e32 v[46:47], v[14:15]
	v_mov_b64_e32 v[30:31], v[14:15]
	v_mov_b64_e32 v[60:61], v[12:13]
	v_mov_b64_e32 v[58:59], v[10:11]
	v_mov_b64_e32 v[56:57], v[8:9]
	v_mov_b64_e32 v[54:55], v[6:7]
	v_mov_b64_e32 v[52:53], v[4:5]
	v_mov_b64_e32 v[50:51], v[2:3]
	v_mov_b64_e32 v[48:49], v[0:1]
	v_mov_b64_e32 v[44:45], v[12:13]
	v_mov_b64_e32 v[42:43], v[10:11]
	v_mov_b64_e32 v[40:41], v[8:9]
	v_mov_b64_e32 v[38:39], v[6:7]
	v_mov_b64_e32 v[36:37], v[4:5]
	v_mov_b64_e32 v[34:35], v[2:3]
	v_mov_b64_e32 v[32:33], v[0:1]
	v_mov_b64_e32 v[28:29], v[12:13]
	v_mov_b64_e32 v[26:27], v[10:11]
	v_mov_b64_e32 v[24:25], v[8:9]
	v_mov_b64_e32 v[22:23], v[6:7]
	v_mov_b64_e32 v[20:21], v[4:5]
	v_mov_b64_e32 v[18:19], v[2:3]
	v_mov_b64_e32 v[16:17], v[0:1]
.LBB0_331:
	s_waitcnt vmcnt(5) lgkmcnt(0)
	s_barrier
	s_add_i32 s4, s31, 1
	s_cmp_lg_u32 s31, 2
	s_cselect_b32 s13, s4, 0
	s_mul_i32 s15, s13, 0x6000
	s_add_i32 s10, s15, 0x6000
	s_cmp_eq_u32 s13, 2
	s_cselect_b64 s[4:5], -1, 0
	s_and_b64 s[8:9], s[4:5], exec
	s_cselect_b32 s8, 0, s10
	s_lshl_b32 vcc_lo, s69, 4
	s_add_i32 vcc_lo, vcc_lo, s8
	s_add_i32 vcc_hi, vcc_lo, 0xc000
	s_mov_b32 m0, vcc_hi
	s_add_i32 vcc_hi, vcc_lo, 0xe000
	global_load_lds_dwordx4 v166, s[98:99]
	s_mov_b32 m0, vcc_hi
	s_add_i32 vcc_hi, vcc_lo, 0x10000
	global_load_lds_dwordx4 v167, s[98:99]
	s_mov_b32 m0, vcc_hi
	s_add_i32 s8, s12, 1
	s_cmp_lg_u32 s12, 2
	s_cselect_b32 s16, s8, 0
	s_lshl_b32 s14, s16, 14
	s_add_i32 s17, s14, 0x4000
	s_cmp_eq_u32 s16, 2
	s_cselect_b64 s[8:9], -1, 0
	s_and_b64 s[10:11], s[8:9], exec
	s_cselect_b32 s10, 0, s17
	global_load_lds_dwordx4 v168, s[98:99]
	s_lshl_b32 vcc_lo, s69, 4
	s_add_i32 vcc_lo, vcc_lo, s10
	s_mov_b32 m0, vcc_lo
	s_add_i32 vcc_hi, vcc_lo, 0x2000
	global_load_lds_dwordx4 v169, s[100:101]
	s_mov_b32 m0, vcc_hi
	s_add_u32 s98, s98, 0x6000
	s_addc_u32 s99, s99, 0
	global_load_lds_dwordx4 v170, s[100:101]
	s_add_u32 s100, s100, 0x4000
	s_addc_u32 s101, s101, 0
	s_mul_i32 s10, s31, 0x6000
	s_add_i32 s10, s10, 0
	v_add_u32_e32 v162, s10, v193
	v_add_u32_e32 v253, s10, v199
	v_add_u32_e32 v252, s10, v200
	v_add_u32_e32 v244, s10, v202
	ds_read_b128 v[64:67], v162 offset:49152
	ds_read_b128 v[68:71], v162 offset:61440
	ds_read_b128 v[228:231], v253 offset:49152
	ds_read_b128 v[232:235], v253 offset:61440
	s_waitcnt lgkmcnt(2)
; __device__ __forceinline__ void finishSM(f32x16& p0, f32x16& p1, float alpha, float& l_reg, bf16x8& pa0, bf16x8& pa1, bf16x8& pa2, bf16x8& pa3) {
;   for (int r = 0; r < 16; ++r) p1[r] = __builtin_amdgcn_exp2f(p1[r]);
;   float ps = 0; for (int r = 0; r < 16; ++r) ps += p0[r]; for (int r = 0; r < 16; ++r) ps += p1[r];
;   { auto rr = __builtin_amdgcn_permlane32_swap(__float_as_uint(ps), __float_as_uint(ps), false, false);
;     ps = __uint_as_float(rr[0]) + __uint_as_float(rr[1]); }
;   l_reg = l_reg * alpha + ps;
;     ...
;   PK4(p0, 0, pa0); PK4(p0, 8, pa1); PK4(p1, 0, pa2); PK4(p1, 8, pa3);
; __device__ __forceinline__ void qkt(f32x16& p0, f32x16& p1, const char* Ks, const bf16x8* qr, int r32, int hi) {
;   p0 = f32x16{}; p1 = f32x16{};
; #pragma unroll
;   for (int d0 = 0; d0 < 12; ++d0) { int cb = (d0 * 16 + hi * 8) * 2;
;     bf16x8 b0 = *reinterpret_cast<const bf16x8*>(Ks + KSWZ(r32, cb));
;     bf16x8 b1 = *reinterpret_cast<const bf16x8*>(Ks + KSWZ(32 + r32, cb));
;     p0 = __builtin_amdgcn_mfma_f32_32x32x16_bf16(b0, qr[d0], p0, 0, 0, 0);
;     p1 = __builtin_amdgcn_mfma_f32_32x32x16_bf16(b1, qr[d0], p1, 0, 0, 0); }
; }
	v_mfma_f32_32x32x16_bf16 v[80:95], v[64:67], v[140:143], 0
	ds_read_b128 v[236:239], v252 offset:49152
	ds_read_b128 v[240:243], v252 offset:61440
	v_exp_f32_e32 v158, v158
	v_exp_f32_e32 v159, v159
	v_exp_f32_e32 v156, v156
	v_exp_f32_e32 v157, v157
	v_mfma_f32_32x32x16_bf16 v[64:79], v[68:71], v[140:143], 0
	v_exp_f32_e32 v154, v154
	v_exp_f32_e32 v155, v155
	v_exp_f32_e32 v163, v153
	v_exp_f32_e32 v206, v150
	v_exp_f32_e32 v227, v151
	v_cvt_pk_bf16_f32 v150, v214, v216
	v_cvt_pk_bf16_f32 v151, v217, v219
	s_waitcnt lgkmcnt(2)
	v_mfma_f32_32x32x16_bf16 v[64:79], v[232:235], v[136:139], v[64:79]
	v_cvt_pk_bf16_f32 v153, v156, v157
	v_mfma_f32_32x32x16_bf16 v[80:95], v[228:231], v[136:139], v[80:95]
	ds_read_b128 v[228:231], v244 offset:49152
	ds_read_b128 v[232:235], v244 offset:61440
	s_waitcnt lgkmcnt(2)
	v_mfma_f32_32x32x16_bf16 v[64:79], v[240:243], v[132:135], v[64:79]
	v_mfma_f32_32x32x16_bf16 v[80:95], v[236:239], v[132:135], v[80:95]
	ds_read_b128 v[236:239], v162 offset:49280
	ds_read_b128 v[240:243], v162 offset:61568
	s_waitcnt lgkmcnt(2)
	v_mfma_f32_32x32x16_bf16 v[64:79], v[232:235], v[128:131], v[64:79]
	v_mfma_f32_32x32x16_bf16 v[80:95], v[228:231], v[128:131], v[80:95]
	ds_read_b128 v[228:231], v253 offset:49280
	ds_read_b128 v[232:235], v253 offset:61568
	s_waitcnt lgkmcnt(2)
	v_mfma_f32_32x32x16_bf16 v[64:79], v[240:243], v[124:127], v[64:79]
	v_mfma_f32_32x32x16_bf16 v[80:95], v[236:239], v[124:127], v[80:95]
	ds_read_b128 v[236:239], v252 offset:49280
	ds_read_b128 v[240:243], v252 offset:61568
	s_waitcnt lgkmcnt(2)
	v_mfma_f32_32x32x16_bf16 v[64:79], v[232:235], v[120:123], v[64:79]
	v_mfma_f32_32x32x16_bf16 v[80:95], v[228:231], v[120:123], v[80:95]
	ds_read_b128 v[228:231], v244 offset:49280
	ds_read_b128 v[232:235], v244 offset:61568
	s_waitcnt lgkmcnt(2)
	v_mfma_f32_32x32x16_bf16 v[64:79], v[240:243], v[116:119], v[64:79]
	v_mfma_f32_32x32x16_bf16 v[80:95], v[236:239], v[116:119], v[80:95]
	ds_read_b128 v[236:239], v162 offset:49408
	ds_read_b128 v[240:243], v162 offset:61696
	s_waitcnt lgkmcnt(2)
	v_mfma_f32_32x32x16_bf16 v[64:79], v[232:235], v[112:115], v[64:79]
	v_mfma_f32_32x32x16_bf16 v[80:95], v[228:231], v[112:115], v[80:95]
	ds_read_b128 v[228:231], v253 offset:49408
	ds_read_b128 v[232:235], v253 offset:61696
	s_waitcnt lgkmcnt(2)
	v_mfma_f32_32x32x16_bf16 v[64:79], v[240:243], v[108:111], v[64:79]
	v_mfma_f32_32x32x16_bf16 v[80:95], v[236:239], v[108:111], v[80:95]
	ds_read_b128 v[236:239], v252 offset:49408
	ds_read_b128 v[240:243], v252 offset:61696
	s_waitcnt lgkmcnt(2)
	v_mfma_f32_32x32x16_bf16 v[64:79], v[232:235], v[104:107], v[64:79]
	v_mfma_f32_32x32x16_bf16 v[80:95], v[228:231], v[104:107], v[80:95]
	ds_read_b128 v[228:231], v244 offset:49408
	ds_read_b128 v[232:235], v244 offset:61696
	v_lshl_add_u32 v252, s12, 14, v190
	ds_read_b64_tr_b16 v[244:245], v252
	ds_read_b64_tr_b16 v[246:247], v252 offset:2048
	ds_read_b64_tr_b16 v[248:249], v252 offset:4096
	ds_read_b64_tr_b16 v[250:251], v252 offset:6144
	v_exp_f32_e32 v162, v152
	v_cvt_pk_bf16_f32 v152, v158, v159
	s_waitcnt lgkmcnt(6)
	v_mfma_f32_32x32x16_bf16 v[64:79], v[240:243], v[100:103], v[64:79]
	v_mfma_f32_32x32x16_bf16 v[80:95], v[236:239], v[100:103], v[80:95]
	s_waitcnt lgkmcnt(4)
	v_mfma_f32_32x32x16_bf16 v[64:79], v[232:235], v[96:99], v[64:79]
	v_exp_f32_e32 v232, v144
	v_add_f32_e32 v144, 0, v218
	v_add_f32_e32 v144, v220, v144
	v_add_f32_e32 v144, v221, v144
	v_add_f32_e32 v144, v222, v144
	v_add_f32_e32 v144, v223, v144
	v_add_f32_e32 v144, v225, v144
	v_add_f32_e32 v144, v224, v144
	v_add_f32_e32 v144, v226, v144
	v_add_f32_e32 v144, v211, v144
	v_add_f32_e32 v144, v212, v144
	v_add_f32_e32 v144, v213, v144
	v_add_f32_e32 v144, v215, v144
	v_add_f32_e32 v144, v214, v144
	v_add_f32_e32 v144, v216, v144
	v_add_f32_e32 v144, v217, v144
	v_add_f32_e32 v144, v219, v144
	v_add_f32_e32 v144, v158, v144
	v_add_f32_e32 v144, v159, v144
	v_add_f32_e32 v144, v156, v144
	v_add_f32_e32 v144, v157, v144
	v_add_f32_e32 v144, v154, v144
	v_add_f32_e32 v144, v155, v144
	v_mfma_f32_32x32x16_bf16 v[80:95], v[228:231], v[96:99], v[80:95]
	v_exp_f32_e32 v228, v148
	v_add_f32_e32 v144, v162, v144
	v_exp_f32_e32 v229, v149
	v_add_f32_e32 v144, v163, v144
	v_exp_f32_e32 v230, v146
	v_add_f32_e32 v144, v206, v144
	v_exp_f32_e32 v231, v147
	v_add_f32_e32 v144, v227, v144
	v_add_f32_e32 v144, v228, v144
	v_exp_f32_e32 v233, v145
	v_add_f32_e32 v144, v229, v144
	v_add_f32_e32 v144, v230, v144
	v_add_f32_e32 v144, v231, v144
	v_add_f32_e32 v144, v232, v144
	v_add_f32_e32 v209, v233, v144
	v_cvt_pk_bf16_f32 v144, v218, v220
	v_cvt_pk_bf16_f32 v145, v221, v222
	v_cvt_pk_bf16_f32 v146, v223, v225
	v_cvt_pk_bf16_f32 v147, v224, v226
	s_nop 0
	v_cvt_pk_bf16_f32 v154, v154, v155
	v_cvt_pk_bf16_f32 v155, v162, v163
	v_cvt_pk_bf16_f32 v148, v211, v212
	v_cvt_pk_bf16_f32 v149, v213, v215
	v_cvt_pk_bf16_f32 v156, v206, v227
	ds_read_b64_tr_b16 v[220:221], v252 offset:8192
	ds_read_b64_tr_b16 v[222:223], v252 offset:10240
	ds_read_b64_tr_b16 v[224:225], v252 offset:12288
	ds_read_b64_tr_b16 v[226:227], v252 offset:14336
	s_waitcnt lgkmcnt(4)
; __device__ __forceinline__ void partialSM(f32x16& p0, f32x16& p1, float& m_reg, float& mn, float& alpha) {
;   constexpr float C = ASCALE * 1.4426950408889634f;
;   float pmax = p0[0]; for (int r = 1; r < 16; ++r) pmax = fmaxf(pmax, p0[r]); for (int r = 0; r < 16; ++r) pmax = fmaxf(pmax, p1[r]);
;   { auto rr = __builtin_amdgcn_permlane32_swap(__float_as_uint(pmax), __float_as_uint(pmax), false, false);
;     pmax = fmaxf(__uint_as_float(rr[0]), __uint_as_float(rr[1])); }
;   if (__builtin_expect(__all(pmax - m_reg <= THR / ASCALE), 1)) { mn = m_reg; alpha = 1.f; }
; template <int D0> __device__ __forceinline__ void pv_one(f32x16& od, int vb, bf16x8 pa0, bf16x8 pa1, bf16x8 pa2, bf16x8 pa3) {
;   const s16x4 l0 = tr_read<v_rd_off(D0, 0, 0)>(vb), h0 = tr_read<v_rd_off(D0, 0, 1)>(vb), l1 = tr_read<v_rd_off(D0, 1, 0)>(vb), h1 = tr_read<v_rd_off(D0, 1, 1)>(vb);
;   const s16x4 l2 = tr_read<v_rd_off(D0, 2, 0)>(vb), h2 = tr_read<v_rd_off(D0, 2, 1)>(vb), l3 = tr_read<v_rd_off(D0, 3, 0)>(vb), h3 = tr_read<v_rd_off(D0, 3, 1)>(vb);
;     ...
;   od = __builtin_amdgcn_mfma_f32_32x32x16_bf16(pa0, PK(l0, h0), od, 0, 0, 0);
;   od = __builtin_amdgcn_mfma_f32_32x32x16_bf16(pa1, PK(l1, h1), od, 0, 0, 0);
;   od = __builtin_amdgcn_mfma_f32_32x32x16_bf16(pa2, PK(l2, h2), od, 0, 0, 0);
;   od = __builtin_amdgcn_mfma_f32_32x32x16_bf16(pa3, PK(l3, h3), od, 0, 0, 0);
;     ...
; }
; __device__ __forceinline__ void pv_d0(f32x16* o, int vb, bf16x8 pa0, bf16x8 pa1, bf16x8 pa2, bf16x8 pa3) {
;   pv_one<0>(o[0], vb, pa0, pa1, pa2, pa3); pv_one<1>(o[1], vb, pa0, pa1, pa2, pa3); pv_one<2>(o[2], vb, pa0, pa1, pa2, pa3); pv_one<3>(o[3], vb, pa0, pa1, pa2, pa3);
	v_mfma_f32_32x32x16_bf16 v[0:15], v[144:147], v[244:247], v[0:15]
	ds_read_b64_tr_b16 v[212:213], v252 offset:512
	ds_read_b64_tr_b16 v[214:215], v252 offset:2560
	v_mfma_f32_32x32x16_bf16 v[0:15], v[148:151], v[248:251], v[0:15]
	ds_read_b64_tr_b16 v[216:217], v252 offset:4608
	ds_read_b64_tr_b16 v[218:219], v252 offset:6656
	v_cvt_pk_bf16_f32 v157, v228, v229
	v_cvt_pk_bf16_f32 v158, v230, v231
	v_cvt_pk_bf16_f32 v159, v232, v233
	s_nop 0
	s_waitcnt lgkmcnt(6)
	v_mfma_f32_32x32x16_bf16 v[0:15], v[152:155], v[220:223], v[0:15]
	ds_read_b64_tr_b16 v[220:221], v252 offset:8704
	ds_read_b64_tr_b16 v[222:223], v252 offset:10752
	v_mov_b32_e32 v210, v209
	s_nop 1
	v_permlane32_swap_b32_e32 v209, v210
	v_mov_b32_e32 v211, 1.0
	s_waitcnt lgkmcnt(6)
	v_mfma_f32_32x32x16_bf16 v[0:15], v[156:159], v[224:227], v[0:15]
	ds_read_b64_tr_b16 v[224:225], v252 offset:12800
	ds_read_b64_tr_b16 v[226:227], v252 offset:14848
	s_waitcnt lgkmcnt(6)
	v_mfma_f32_32x32x16_bf16 v[48:63], v[144:147], v[212:215], v[48:63]
	ds_read_b64_tr_b16 v[212:213], v252 offset:1024
	ds_read_b64_tr_b16 v[214:215], v252 offset:3072
	s_waitcnt lgkmcnt(6)
	v_mfma_f32_32x32x16_bf16 v[48:63], v[148:151], v[216:219], v[48:63]
	ds_read_b64_tr_b16 v[216:217], v252 offset:5120
	ds_read_b64_tr_b16 v[218:219], v252 offset:7168
	s_waitcnt lgkmcnt(6)
	v_mfma_f32_32x32x16_bf16 v[48:63], v[152:155], v[220:223], v[48:63]
	ds_read_b64_tr_b16 v[220:221], v252 offset:9216
	ds_read_b64_tr_b16 v[222:223], v252 offset:11264
	s_waitcnt lgkmcnt(6)
	v_mfma_f32_32x32x16_bf16 v[48:63], v[156:159], v[224:227], v[48:63]
	ds_read_b64_tr_b16 v[224:225], v252 offset:13312
	ds_read_b64_tr_b16 v[226:227], v252 offset:15360
	s_waitcnt lgkmcnt(6)
	v_mfma_f32_32x32x16_bf16 v[32:47], v[144:147], v[212:215], v[32:47]
	ds_read_b64_tr_b16 v[212:213], v252 offset:1536
	ds_read_b64_tr_b16 v[214:215], v252 offset:3584
	s_waitcnt lgkmcnt(6)
	v_mfma_f32_32x32x16_bf16 v[32:47], v[148:151], v[216:219], v[32:47]
	ds_read_b64_tr_b16 v[216:217], v252 offset:5632
	ds_read_b64_tr_b16 v[218:219], v252 offset:7680
	s_waitcnt lgkmcnt(6)
	v_mfma_f32_32x32x16_bf16 v[32:47], v[152:155], v[220:223], v[32:47]
	ds_read_b64_tr_b16 v[220:221], v252 offset:9728
	ds_read_b64_tr_b16 v[222:223], v252 offset:11776
	s_waitcnt lgkmcnt(6)
	v_mfma_f32_32x32x16_bf16 v[32:47], v[156:159], v[224:227], v[32:47]
	ds_read_b64_tr_b16 v[224:225], v252 offset:13824
	ds_read_b64_tr_b16 v[226:227], v252 offset:15872
	s_waitcnt lgkmcnt(6)
	v_mfma_f32_32x32x16_bf16 v[16:31], v[144:147], v[212:215], v[16:31]
	v_max_f32_e32 v144, v81, v81
	v_max_f32_e32 v145, v80, v80
	v_max_f32_e32 v144, v145, v144
	v_max3_f32 v144, v144, v82, v83
	v_max3_f32 v144, v144, v84, v85
	v_max3_f32 v144, v144, v86, v87
	v_max3_f32 v144, v144, v88, v89
	s_waitcnt lgkmcnt(4)
	v_mfma_f32_32x32x16_bf16 v[16:31], v[148:151], v[216:219], v[16:31]
	v_max3_f32 v144, v144, v90, v91
	v_max3_f32 v144, v144, v92, v93
	v_max3_f32 v144, v144, v94, v95
	v_max3_f32 v144, v144, v64, v65
	v_max3_f32 v144, v144, v66, v67
	v_max3_f32 v144, v144, v68, v69
	v_max3_f32 v144, v144, v70, v71
	s_waitcnt lgkmcnt(2)
	v_mfma_f32_32x32x16_bf16 v[16:31], v[152:155], v[220:223], v[16:31]
	v_max3_f32 v144, v144, v72, v73
	v_max3_f32 v144, v144, v74, v75
	v_max3_f32 v144, v144, v76, v77
	v_max3_f32 v144, v144, v78, v79
	v_mov_b32_e32 v145, v144
	s_nop 1
	v_permlane32_swap_b32_e32 v144, v145
	s_waitcnt lgkmcnt(0)
	v_mfma_f32_32x32x16_bf16 v[16:31], v[156:159], v[224:227], v[16:31]
	v_max_f32_e32 v145, v145, v145
	v_max_f32_e32 v144, v144, v144
	v_max_f32_e32 v144, v144, v145
	v_sub_f32_e32 v145, v144, v191
	v_cmp_ge_f32_e32 vcc, s35, v145
	s_cmp_eq_u64 vcc, exec
	s_cbranch_scc0 .LBB0_344
	v_cmp_gt_f32_e32 vcc, 1.0, v211
	s_cbranch_vccz .LBB0_336

; #define ISSUE_K(t, slot) do { const char* kg_ = (const char*)(Kh + (long)(t) * (KVBLK * 192)); char* kl_ = K_lds + (slot) * SHM_K + tid * 16; \
;     DMA16(kg_ + kso0, kl_); DMA16(kg_ + kso1, kl_ + 8192); DMA16(kg_ + kso2, kl_ + 16384); } while (0)
; #define ISSUE_V(t, slot) do { const char* vg_ = (const char*)(Vh + (long)(t) * (KVBLK * 128)); char* vl_ = V_lds + (slot) * SHM_V + tid * 16; \
;     DMA16(vg_ + vso0, vl_); DMA16(vg_ + vso1, vl_ + 8192); } while (0)
; #define TBAR(n) do { asm volatile("s_waitcnt vmcnt(" #n ") lgkmcnt(0)" ::: "memory"); __builtin_amdgcn_s_barrier(); SBAR(); } while (0)
; __device__ __forceinline__ void partialSM(f32x16& p0, f32x16& p1, float& m_reg, float& mn, float& alpha) {
;     ...
;   else { mn = fmaxf(m_reg, pmax); alpha = __builtin_amdgcn_exp2f((m_reg - mn) * C); m_reg = mn; }
;   float mnC = -mn * C;
;   for (int r = 0; r < 16; ++r) p0[r] = fmaf(p0[r], C, mnC); for (int r = 0; r < 16; ++r) p1[r] = fmaf(p1[r], C, mnC);
;   for (int r = 0; r < 16; ++r) p0[r] = __builtin_amdgcn_exp2f(p0[r]);
; __device__ __forceinline__ void attn_body(const u16* __restrict__ Qb, const u16* __restrict__ Kh, const u16* __restrict__ Vh,
;                                           u16* __restrict__ Ob, int seq, int wvs) {
;     ...
;     TBAR(5);
;     if (j + 3 < NT) ISSUE_K(j + 3, NEXT3(NEXT3(sK)));
;     ISSUE_V(j + 2, NEXT3(NEXT3(sV)));
;     qkt(pA0, pA1, K_lds + sK * SHM_K, qr, r32, hi);
;     finishSM(pB0, pB1, alB, l_reg, pa0, pa1, pa2, pa3);
;     pv_d0(o, vb0 + sV * SHM_V, pa0, pa1, pa2, pa3); partialSM(pA0, pA1, m_reg, mnA, alA);
.LBB0_338:
	s_add_u32 s98, s98, 0x6000
	s_addc_u32 s99, s99, 0
	s_add_i32 s16, s16, 1
	s_and_b64 s[8:9], s[8:9], exec
	s_cselect_b32 s12, 0, s16
	s_lshl_b32 s17, s12, 14
	s_add_i32 s8, s17, 0x4000
	s_cmp_lg_u32 s12, 2
	v_mul_f32_e32 v180, 0xbdd53b94, v191
	s_cselect_b32 s16, s8, 0
	v_fmamk_f32 v221, v66, 0x3dd53b94, v180
	v_fmamk_f32 v219, v64, 0x3dd53b94, v180
	v_fmamk_f32 v220, v65, 0x3dd53b94, v180
	s_lshl_b32 vcc_lo, s69, 4
	s_add_i32 vcc_lo, vcc_lo, s16
	s_mov_b32 m0, vcc_lo
	s_add_i32 vcc_hi, vcc_lo, 0x2000
	global_load_lds_dwordx4 v169, s[100:101]
	s_mov_b32 m0, vcc_hi
	s_add_i32 s8, s15, 0
	v_fmamk_f32 v218, v68, 0x3dd53b94, v180
	global_load_lds_dwordx4 v170, s[100:101]
	s_add_u32 s100, s100, 0x4000
	s_addc_u32 s101, s101, 0
	v_add_u32_e32 v68, s8, v193
	v_fmamk_f32 v217, v67, 0x3dd53b94, v180
	v_fmamk_f32 v181, v69, 0x3dd53b94, v180
	v_fmamk_f32 v182, v70, 0x3dd53b94, v180
	v_fmamk_f32 v183, v71, 0x3dd53b94, v180
	ds_read_b128 v[64:67], v68 offset:49152
	ds_read_b128 v[68:71], v68 offset:61440
	v_add_u32_e32 v162, s8, v193
	v_add_u32_e32 v253, s8, v199
	v_add_u32_e32 v252, s8, v200
	v_add_u32_e32 v244, s8, v202
	ds_read_b128 v[176:179], v253 offset:49152
	ds_read_b128 v[222:225], v253 offset:61440
	v_fmamk_f32 v80, v80, 0x3dd53b94, v180
	v_fmamk_f32 v81, v81, 0x3dd53b94, v180
	v_fmamk_f32 v82, v82, 0x3dd53b94, v180
	v_fmamk_f32 v83, v83, 0x3dd53b94, v180
	v_fmamk_f32 v84, v84, 0x3dd53b94, v180
	v_fmamk_f32 v85, v85, 0x3dd53b94, v180
	v_fmamk_f32 v86, v86, 0x3dd53b94, v180
	v_fmamk_f32 v87, v87, 0x3dd53b94, v180
	v_fmamk_f32 v88, v88, 0x3dd53b94, v180
	v_fmamk_f32 v89, v89, 0x3dd53b94, v180
	v_fmamk_f32 v90, v90, 0x3dd53b94, v180
	v_fmamk_f32 v91, v91, 0x3dd53b94, v180
	v_fmamk_f32 v92, v92, 0x3dd53b94, v180
	v_fmamk_f32 v93, v93, 0x3dd53b94, v180
	v_fmamk_f32 v94, v94, 0x3dd53b94, v180
	v_fmamk_f32 v95, v95, 0x3dd53b94, v180
	v_exp_f32_e32 v144, v80
	v_exp_f32_e32 v145, v81
	v_exp_f32_e32 v146, v82
	v_exp_f32_e32 v156, v83
	v_exp_f32_e32 v147, v84
	v_exp_f32_e32 v157, v85
	v_exp_f32_e32 v158, v86
	v_exp_f32_e32 v159, v87
	v_exp_f32_e32 v148, v88
	v_exp_f32_e32 v150, v89
	v_exp_f32_e32 v149, v90
	v_exp_f32_e32 v151, v91
	v_exp_f32_e32 v152, v92
	v_exp_f32_e32 v153, v93
	v_exp_f32_e32 v154, v94
	v_exp_f32_e32 v155, v95
	s_waitcnt lgkmcnt(2)
	v_mfma_f32_32x32x16_bf16 v[80:95], v[64:67], v[140:143], 0
	ds_read_b128 v[236:239], v252 offset:49152
	ds_read_b128 v[240:243], v252 offset:61440
	v_fmamk_f32 v184, v72, 0x3dd53b94, v180
	v_fmamk_f32 v185, v73, 0x3dd53b94, v180
	v_fmamk_f32 v212, v74, 0x3dd53b94, v180
	v_fmamk_f32 v213, v75, 0x3dd53b94, v180
	v_fmamk_f32 v214, v76, 0x3dd53b94, v180
	v_fmamk_f32 v215, v77, 0x3dd53b94, v180
	v_fmamk_f32 v216, v78, 0x3dd53b94, v180
	v_fmac_f32_e32 v180, 0x3dd53b94, v79
	v_mfma_f32_32x32x16_bf16 v[64:79], v[68:71], v[140:143], 0
	v_exp_f32_e32 v163, v220
	v_exp_f32_e32 v206, v218
	v_exp_f32_e32 v181, v181
	v_exp_f32_e32 v182, v182
	v_exp_f32_e32 v183, v183
	s_waitcnt lgkmcnt(2)
	v_mfma_f32_32x32x16_bf16 v[80:95], v[176:179], v[136:139], v[80:95]
	v_exp_f32_e32 v184, v184
	v_exp_f32_e32 v185, v185
	v_exp_f32_e32 v212, v212
	v_exp_f32_e32 v213, v213
	v_exp_f32_e32 v214, v214
	v_exp_f32_e32 v215, v215
	v_exp_f32_e32 v216, v216
	v_mfma_f32_32x32x16_bf16 v[64:79], v[222:225], v[136:139], v[64:79]
	ds_read_b128 v[176:179], v244 offset:49152
	ds_read_b128 v[222:225], v244 offset:61440
	v_exp_f32_e32 v180, v180
	s_waitcnt lgkmcnt(2)
	v_mfma_f32_32x32x16_bf16 v[80:95], v[236:239], v[132:135], v[80:95]
	v_mfma_f32_32x32x16_bf16 v[64:79], v[240:243], v[132:135], v[64:79]
	ds_read_b128 v[236:239], v162 offset:49280
	ds_read_b128 v[240:243], v162 offset:61568
	s_waitcnt lgkmcnt(2)
	v_mfma_f32_32x32x16_bf16 v[80:95], v[176:179], v[128:131], v[80:95]
	v_mfma_f32_32x32x16_bf16 v[64:79], v[222:225], v[128:131], v[64:79]
	ds_read_b128 v[176:179], v253 offset:49280
	ds_read_b128 v[222:225], v253 offset:61568
	s_waitcnt lgkmcnt(2)
	v_mfma_f32_32x32x16_bf16 v[80:95], v[236:239], v[124:127], v[80:95]
	v_mfma_f32_32x32x16_bf16 v[64:79], v[240:243], v[124:127], v[64:79]
	ds_read_b128 v[236:239], v252 offset:49280
	ds_read_b128 v[240:243], v252 offset:61568
	s_waitcnt lgkmcnt(2)
	v_mfma_f32_32x32x16_bf16 v[80:95], v[176:179], v[120:123], v[80:95]
	v_mfma_f32_32x32x16_bf16 v[64:79], v[222:225], v[120:123], v[64:79]
	ds_read_b128 v[176:179], v244 offset:49280
	ds_read_b128 v[222:225], v244 offset:61568
	s_waitcnt lgkmcnt(2)
	v_mfma_f32_32x32x16_bf16 v[80:95], v[236:239], v[116:119], v[80:95]
	v_mfma_f32_32x32x16_bf16 v[64:79], v[240:243], v[116:119], v[64:79]
	ds_read_b128 v[236:239], v162 offset:49408
	ds_read_b128 v[240:243], v162 offset:61696
	s_waitcnt lgkmcnt(2)
	v_mfma_f32_32x32x16_bf16 v[80:95], v[176:179], v[112:115], v[80:95]
	v_mfma_f32_32x32x16_bf16 v[64:79], v[222:225], v[112:115], v[64:79]
	ds_read_b128 v[176:179], v253 offset:49408
	ds_read_b128 v[222:225], v253 offset:61696
	s_waitcnt lgkmcnt(2)
	v_mfma_f32_32x32x16_bf16 v[80:95], v[236:239], v[108:111], v[80:95]
	v_mfma_f32_32x32x16_bf16 v[64:79], v[240:243], v[108:111], v[64:79]
	ds_read_b128 v[236:239], v252 offset:49408
	ds_read_b128 v[240:243], v252 offset:61696
	s_waitcnt lgkmcnt(2)
	v_mfma_f32_32x32x16_bf16 v[80:95], v[176:179], v[104:107], v[80:95]
	v_mfma_f32_32x32x16_bf16 v[64:79], v[222:225], v[104:107], v[64:79]
	ds_read_b128 v[176:179], v244 offset:49408
	ds_read_b128 v[222:225], v244 offset:61696
	v_add_u32_e32 v252, s14, v190
	ds_read_b64_tr_b16 v[244:245], v252
	ds_read_b64_tr_b16 v[246:247], v252 offset:2048
	ds_read_b64_tr_b16 v[248:249], v252 offset:4096
	ds_read_b64_tr_b16 v[250:251], v252 offset:6144
	v_exp_f32_e32 v162, v219
	s_waitcnt lgkmcnt(6)
; __device__ __forceinline__ void finishSM(f32x16& p0, f32x16& p1, float alpha, float& l_reg, bf16x8& pa0, bf16x8& pa1, bf16x8& pa2, bf16x8& pa3) {
;   for (int r = 0; r < 16; ++r) p1[r] = __builtin_amdgcn_exp2f(p1[r]);
;   float ps = 0; for (int r = 0; r < 16; ++r) ps += p0[r]; for (int r = 0; r < 16; ++r) ps += p1[r];
;   { auto rr = __builtin_amdgcn_permlane32_swap(__float_as_uint(ps), __float_as_uint(ps), false, false);
;     ps = __uint_as_float(rr[0]) + __uint_as_float(rr[1]); }
;   l_reg = l_reg * alpha + ps;
;     ...
;   PK4(p0, 0, pa0); PK4(p0, 8, pa1); PK4(p1, 0, pa2); PK4(p1, 8, pa3);
;     ...
; }
; __device__ __forceinline__ void qkt(f32x16& p0, f32x16& p1, const char* Ks, const bf16x8* qr, int r32, int hi) {
;   p0 = f32x16{}; p1 = f32x16{};
; #pragma unroll
;   for (int d0 = 0; d0 < 12; ++d0) { int cb = (d0 * 16 + hi * 8) * 2;
;     bf16x8 b0 = *reinterpret_cast<const bf16x8*>(Ks + KSWZ(r32, cb));
;     bf16x8 b1 = *reinterpret_cast<const bf16x8*>(Ks + KSWZ(32 + r32, cb));
;     p0 = __builtin_amdgcn_mfma_f32_32x32x16_bf16(b0, qr[d0], p0, 0, 0, 0);
;     p1 = __builtin_amdgcn_mfma_f32_32x32x16_bf16(b1, qr[d0], p1, 0, 0, 0); }
; }
; __device__ __forceinline__ int v_st(int k, int c) { const int kk = (k & ~0xC) | ((k & 4) << 1) | ((k & 8) >> 1); return ((kk >> 3) * 4 + (c >> 5)) * 512 + ((kk & 7) * 32 + (c & 31)) * 2; }
; __device__ __forceinline__ int v_rd_base(int lane) { return ((lane & 3) << 3) | (((lane >> 2) & 3) << 6) | (((lane >> 4) & 1) << 5) | (((lane >> 5) & 1) << 8); }
; template <int OFF> __device__ __forceinline__ s16x4 tr_read(int vb) {
;   return __builtin_amdgcn_ds_read_tr16_b64_v4i16((lds_s16x4*)(uintptr_t)(unsigned)(vb + OFF));
; }
; template <int D0> __device__ __forceinline__ void pv_one(f32x16& od, int vb, bf16x8 pa0, bf16x8 pa1, bf16x8 pa2, bf16x8 pa3) {
;   const s16x4 l0 = tr_read<v_rd_off(D0, 0, 0)>(vb), h0 = tr_read<v_rd_off(D0, 0, 1)>(vb), l1 = tr_read<v_rd_off(D0, 1, 0)>(vb), h1 = tr_read<v_rd_off(D0, 1, 1)>(vb);
;   const s16x4 l2 = tr_read<v_rd_off(D0, 2, 0)>(vb), h2 = tr_read<v_rd_off(D0, 2, 1)>(vb), l3 = tr_read<v_rd_off(D0, 3, 0)>(vb), h3 = tr_read<v_rd_off(D0, 3, 1)>(vb);
;     ...
;   od = __builtin_amdgcn_mfma_f32_32x32x16_bf16(pa0, PK(l0, h0), od, 0, 0, 0);
;   od = __builtin_amdgcn_mfma_f32_32x32x16_bf16(pa1, PK(l1, h1), od, 0, 0, 0);
;   od = __builtin_amdgcn_mfma_f32_32x32x16_bf16(pa2, PK(l2, h2), od, 0, 0, 0);
	v_mfma_f32_32x32x16_bf16 v[80:95], v[236:239], v[100:103], v[80:95]
	v_mfma_f32_32x32x16_bf16 v[64:79], v[240:243], v[100:103], v[64:79]
	s_waitcnt lgkmcnt(4)
	v_mfma_f32_32x32x16_bf16 v[80:95], v[176:179], v[96:99], v[80:95]
	v_add_f32_e32 v177, 0, v144
	v_add_f32_e32 v177, v145, v177
	v_add_f32_e32 v177, v146, v177
	v_add_f32_e32 v177, v156, v177
	v_add_f32_e32 v177, v147, v177
	v_add_f32_e32 v177, v157, v177
	v_add_f32_e32 v177, v158, v177
	v_add_f32_e32 v177, v159, v177
	v_add_f32_e32 v177, v148, v177
	v_add_f32_e32 v177, v150, v177
	v_add_f32_e32 v177, v149, v177
	v_add_f32_e32 v177, v151, v177
	v_add_f32_e32 v177, v152, v177
	v_add_f32_e32 v177, v153, v177
	v_exp_f32_e32 v176, v221
	v_add_f32_e32 v177, v154, v177
	v_exp_f32_e32 v179, v217
	v_add_f32_e32 v177, v155, v177
	v_add_f32_e32 v177, v162, v177
	v_add_f32_e32 v177, v163, v177
	v_add_f32_e32 v177, v176, v177
	v_add_f32_e32 v177, v179, v177
	v_add_f32_e32 v177, v206, v177
	v_add_f32_e32 v177, v181, v177
	v_add_f32_e32 v177, v182, v177
	v_add_f32_e32 v177, v183, v177
	v_add_f32_e32 v177, v184, v177
	v_add_f32_e32 v177, v185, v177
	v_cvt_pk_bf16_f32 v144, v144, v145
	v_cvt_pk_bf16_f32 v145, v146, v156
	v_cvt_pk_bf16_f32 v146, v147, v157
	v_cvt_pk_bf16_f32 v147, v158, v159
	v_add_f32_e32 v177, v212, v177
	v_add_f32_e32 v177, v213, v177
	v_add_f32_e32 v177, v214, v177
	v_add_f32_e32 v177, v215, v177
	v_add_f32_e32 v177, v216, v177
	v_cvt_pk_bf16_f32 v148, v148, v150
	v_cvt_pk_bf16_f32 v150, v152, v153
	v_cvt_pk_bf16_f32 v152, v162, v163
	v_mfma_f32_32x32x16_bf16 v[64:79], v[222:225], v[96:99], v[64:79]
	v_add_f32_e32 v177, v180, v177
	v_cvt_pk_bf16_f32 v149, v149, v151
	v_cvt_pk_bf16_f32 v151, v154, v155
	v_cvt_pk_bf16_f32 v154, v206, v181
	v_cvt_pk_bf16_f32 v155, v182, v183
	v_cvt_pk_bf16_f32 v157, v212, v213
	v_cvt_pk_bf16_f32 v158, v214, v215
	v_cvt_pk_bf16_f32 v159, v216, v180
	ds_read_b64_tr_b16 v[216:217], v252 offset:8192
	ds_read_b64_tr_b16 v[218:219], v252 offset:10240
	ds_read_b64_tr_b16 v[220:221], v252 offset:12288
	ds_read_b64_tr_b16 v[222:223], v252 offset:14336
	s_waitcnt lgkmcnt(4)
	v_mfma_f32_32x32x16_bf16 v[0:15], v[144:147], v[244:247], v[0:15]
	ds_read_b64_tr_b16 v[180:181], v252 offset:512
	ds_read_b64_tr_b16 v[182:183], v252 offset:2560
	v_cvt_pk_bf16_f32 v153, v176, v179
	v_mfma_f32_32x32x16_bf16 v[0:15], v[148:151], v[248:251], v[0:15]
	ds_read_b64_tr_b16 v[212:213], v252 offset:4608
	ds_read_b64_tr_b16 v[214:215], v252 offset:6656
	v_cvt_pk_bf16_f32 v156, v184, v185
	s_nop 1
	s_waitcnt lgkmcnt(6)
	v_mfma_f32_32x32x16_bf16 v[0:15], v[152:155], v[216:219], v[0:15]
	ds_read_b64_tr_b16 v[216:217], v252 offset:8704
	ds_read_b64_tr_b16 v[218:219], v252 offset:10752
	v_mov_b32_e32 v178, v177
	s_nop 1
	v_permlane32_swap_b32_e32 v177, v178
	s_waitcnt lgkmcnt(6)
	v_mfma_f32_32x32x16_bf16 v[0:15], v[156:159], v[220:223], v[0:15]
	ds_read_b64_tr_b16 v[220:221], v252 offset:12800
	ds_read_b64_tr_b16 v[222:223], v252 offset:14848
	s_waitcnt lgkmcnt(6)
	v_mfma_f32_32x32x16_bf16 v[48:63], v[144:147], v[180:183], v[48:63]
	ds_read_b64_tr_b16 v[180:181], v252 offset:1024
	ds_read_b64_tr_b16 v[182:183], v252 offset:3072
	s_waitcnt lgkmcnt(6)
	v_mfma_f32_32x32x16_bf16 v[48:63], v[148:151], v[212:215], v[48:63]
	ds_read_b64_tr_b16 v[212:213], v252 offset:5120
	ds_read_b64_tr_b16 v[214:215], v252 offset:7168
	s_waitcnt lgkmcnt(6)
	v_mfma_f32_32x32x16_bf16 v[48:63], v[152:155], v[216:219], v[48:63]
	ds_read_b64_tr_b16 v[216:217], v252 offset:9216
	ds_read_b64_tr_b16 v[218:219], v252 offset:11264
	s_waitcnt lgkmcnt(6)
	v_mfma_f32_32x32x16_bf16 v[48:63], v[156:159], v[220:223], v[48:63]
	ds_read_b64_tr_b16 v[220:221], v252 offset:13312
	ds_read_b64_tr_b16 v[222:223], v252 offset:15360
	s_waitcnt lgkmcnt(6)
	v_mfma_f32_32x32x16_bf16 v[32:47], v[144:147], v[180:183], v[32:47]
	ds_read_b64_tr_b16 v[180:181], v252 offset:1536
	ds_read_b64_tr_b16 v[182:183], v252 offset:3584
	s_waitcnt lgkmcnt(6)
	v_mfma_f32_32x32x16_bf16 v[32:47], v[148:151], v[212:215], v[32:47]
	ds_read_b64_tr_b16 v[212:213], v252 offset:5632
	ds_read_b64_tr_b16 v[214:215], v252 offset:7680
	s_waitcnt lgkmcnt(6)
	v_mfma_f32_32x32x16_bf16 v[32:47], v[152:155], v[216:219], v[32:47]
	ds_read_b64_tr_b16 v[216:217], v252 offset:9728
	ds_read_b64_tr_b16 v[218:219], v252 offset:11776
	s_waitcnt lgkmcnt(6)
	v_mfma_f32_32x32x16_bf16 v[32:47], v[156:159], v[220:223], v[32:47]
	ds_read_b64_tr_b16 v[220:221], v252 offset:13824
	ds_read_b64_tr_b16 v[222:223], v252 offset:15872
	s_waitcnt lgkmcnt(6)
	v_mfma_f32_32x32x16_bf16 v[16:31], v[144:147], v[180:183], v[16:31]
	v_max_f32_e32 v144, v81, v81
	v_max_f32_e32 v145, v80, v80
	v_max_f32_e32 v144, v145, v144
	v_max3_f32 v144, v144, v82, v83
	v_max3_f32 v144, v144, v84, v85
	v_max3_f32 v144, v144, v86, v87
	v_max3_f32 v144, v144, v88, v89
	v_max3_f32 v144, v144, v90, v91
	v_max3_f32 v144, v144, v92, v93
	s_waitcnt lgkmcnt(4)
	v_mfma_f32_32x32x16_bf16 v[16:31], v[148:151], v[212:215], v[16:31]
	v_max3_f32 v144, v144, v94, v95
	v_max3_f32 v144, v144, v64, v65
	v_max3_f32 v144, v144, v66, v67
	v_max3_f32 v144, v144, v68, v69
	v_max3_f32 v144, v144, v70, v71
	v_max3_f32 v144, v144, v72, v73
	v_max3_f32 v144, v144, v74, v75
	v_max3_f32 v144, v144, v76, v77
	s_waitcnt lgkmcnt(2)
	v_mfma_f32_32x32x16_bf16 v[16:31], v[152:155], v[216:219], v[16:31]
	v_max3_f32 v144, v144, v78, v79
	v_mov_b32_e32 v145, v144
	s_nop 1
	v_permlane32_swap_b32_e32 v144, v145
	v_max_f32_e32 v145, v145, v145
	v_max_f32_e32 v144, v144, v144
	v_max_f32_e32 v144, v144, v145
	v_sub_f32_e32 v145, v144, v191
	v_cmp_ge_f32_e32 vcc, s35, v145
	v_max_f32_e32 v145, v191, v191
	v_max_f32_e32 v144, v145, v144
	s_waitcnt lgkmcnt(0)
	v_mfma_f32_32x32x16_bf16 v[16:31], v[156:159], v[220:223], v[16:31]
	v_sub_f32_e32 v145, v191, v144
	v_mul_f32_e32 v145, 0x3dd53b94, v145
	v_exp_f32_e32 v145, v145
	s_cmp_eq_u64 vcc, exec
	s_cselect_b64 s[8:9], -1, 0
	v_cndmask_b32_e64 v176, v145, 1.0, s[8:9]
	v_cmp_gt_f32_e32 vcc, 1.0, v176
	s_cbranch_vccz .LBB0_342
	s_and_saveexec_b64 s[14:15], s[6:7]
	ds_write_b32 v188, v176 offset:128
	s_or_b64 exec, exec, s[14:15]
	s_waitcnt lgkmcnt(0)
	v_add_u32_e32 v145, v165, v160
	ds_read_b128 v[146:149], v145 offset:224
	ds_read_b128 v[150:153], v145 offset:192
	ds_read_b128 v[154:157], v145 offset:160
	ds_read_b128 v[180:183], v145 offset:128
	s_waitcnt lgkmcnt(0)
	v_pk_mul_f32 v[12:13], v[12:13], v[146:147]
	v_pk_mul_f32 v[8:9], v[8:9], v[150:151]
	v_pk_mul_f32 v[4:5], v[4:5], v[154:155]
	v_pk_mul_f32 v[14:15], v[14:15], v[148:149]
	v_pk_mul_f32 v[10:11], v[10:11], v[152:153]
	v_pk_mul_f32 v[6:7], v[6:7], v[156:157]
	v_pk_mul_f32 v[2:3], v[2:3], v[182:183]
	v_pk_mul_f32 v[0:1], v[0:1], v[180:181]
	v_pk_mul_f32 v[60:61], v[60:61], v[146:147]
	v_pk_mul_f32 v[56:57], v[56:57], v[150:151]
	v_pk_mul_f32 v[52:53], v[52:53], v[154:155]
	v_pk_mul_f32 v[62:63], v[62:63], v[148:149]
	v_pk_mul_f32 v[58:59], v[58:59], v[152:153]
	v_pk_mul_f32 v[54:55], v[54:55], v[156:157]
	v_pk_mul_f32 v[50:51], v[50:51], v[182:183]
	v_pk_mul_f32 v[48:49], v[48:49], v[180:181]
	v_pk_mul_f32 v[44:45], v[44:45], v[146:147]
	v_pk_mul_f32 v[40:41], v[40:41], v[150:151]
	v_pk_mul_f32 v[36:37], v[36:37], v[154:155]
	v_pk_mul_f32 v[46:47], v[46:47], v[148:149]
	v_pk_mul_f32 v[42:43], v[42:43], v[152:153]
	v_pk_mul_f32 v[38:39], v[38:39], v[156:157]
	v_pk_mul_f32 v[34:35], v[34:35], v[182:183]
	v_pk_mul_f32 v[32:33], v[32:33], v[180:181]
	v_pk_mul_f32 v[28:29], v[28:29], v[146:147]
	v_pk_mul_f32 v[24:25], v[24:25], v[150:151]
	v_pk_mul_f32 v[20:21], v[20:21], v[154:155]
	v_pk_mul_f32 v[30:31], v[30:31], v[148:149]
	v_pk_mul_f32 v[26:27], v[26:27], v[152:153]
	v_pk_mul_f32 v[22:23], v[22:23], v[156:157]
	v_pk_mul_f32 v[18:19], v[18:19], v[182:183]
	v_pk_mul_f32 v[16:17], v[16:17], v[180:181]

; #define SBAR() __builtin_amdgcn_sched_barrier(0)
; #define TBAR(n) do { asm volatile("s_waitcnt vmcnt(" #n ") lgkmcnt(0)" ::: "memory"); __builtin_amdgcn_s_barrier(); SBAR(); } while (0)
; __device__ __forceinline__ void finishSM(f32x16& p0, f32x16& p1, float alpha, float& l_reg, bf16x8& pa0, bf16x8& pa1, bf16x8& pa2, bf16x8& pa3) {
;   for (int r = 0; r < 16; ++r) p1[r] = __builtin_amdgcn_exp2f(p1[r]);
;   float ps = 0; for (int r = 0; r < 16; ++r) ps += p0[r]; for (int r = 0; r < 16; ++r) ps += p1[r];
;   { auto rr = __builtin_amdgcn_permlane32_swap(__float_as_uint(ps), __float_as_uint(ps), false, false);
;     ps = __uint_as_float(rr[0]) + __uint_as_float(rr[1]); }
;   l_reg = l_reg * alpha + ps;
;     ...
;   PK4(p0, 0, pa0); PK4(p0, 8, pa1); PK4(p1, 0, pa2); PK4(p1, 8, pa3);
; __device__ __forceinline__ void attn_body(const u16* __restrict__ Qb, const u16* __restrict__ Kh, const u16* __restrict__ Vh,
;                                           u16* __restrict__ Ob, int seq, int wvs) {
;     ...
;   TBAR(2);
;   SBAR(); qkt(pB0, pB1, K_lds + sK * SHM_K, qr, r32, hi);
;   finishSM(pA0, pA1, alA, l_reg, pa0, pa1, pa2, pa3); SBAR();
;   pv_d0(o, vb0 + sV * SHM_V, pa0, pa1, pa2, pa3); partialSM(pB0, pB1, m_reg, mnB, alB);
.LBB0_372:
	s_waitcnt vmcnt(2) lgkmcnt(0)
	s_barrier
	s_mul_i32 s4, s31, 0x6000
	s_add_i32 s4, s4, 0
	v_add_u32_e32 v68, s4, v193
	ds_read_b128 v[64:67], v68 offset:49152
	ds_read_b128 v[68:71], v68 offset:61440
	v_add_u32_e32 v162, s4, v199
	s_waitcnt lgkmcnt(0)
	v_mfma_f32_32x32x16_bf16 v[80:95], v[64:67], v[140:143], 0
	v_mfma_f32_32x32x16_bf16 v[64:79], v[68:71], v[140:143], 0
	ds_read_b128 v[140:143], v162 offset:49152
	ds_read_b128 v[166:169], v162 offset:61440
	s_waitcnt lgkmcnt(0)
	v_mfma_f32_32x32x16_bf16 v[80:95], v[140:143], v[136:139], v[80:95]
	v_add_u32_e32 v140, s4, v200
	v_mfma_f32_32x32x16_bf16 v[64:79], v[166:169], v[136:139], v[64:79]
	ds_read_b128 v[136:139], v140 offset:49152
	ds_read_b128 v[140:143], v140 offset:61440
	s_waitcnt lgkmcnt(0)
	v_mfma_f32_32x32x16_bf16 v[80:95], v[136:139], v[132:135], v[80:95]
	v_add_u32_e32 v136, s4, v202
	v_mfma_f32_32x32x16_bf16 v[64:79], v[140:143], v[132:135], v[64:79]
	ds_read_b128 v[132:135], v136 offset:49152
	ds_read_b128 v[136:139], v136 offset:61440
	s_waitcnt lgkmcnt(0)
	v_mfma_f32_32x32x16_bf16 v[80:95], v[132:135], v[128:131], v[80:95]
	v_add_u32_e32 v132, s4, v207
	v_mfma_f32_32x32x16_bf16 v[64:79], v[136:139], v[128:131], v[64:79]
	ds_read_b128 v[128:131], v132 offset:49152
	ds_read_b128 v[132:135], v132 offset:61440
	s_waitcnt lgkmcnt(0)
	v_mfma_f32_32x32x16_bf16 v[80:95], v[128:131], v[124:127], v[80:95]
	v_add_u32_e32 v128, s4, v203
	v_mfma_f32_32x32x16_bf16 v[64:79], v[132:135], v[124:127], v[64:79]
	ds_read_b128 v[124:127], v128 offset:49152
	ds_read_b128 v[128:131], v128 offset:61440
	s_waitcnt lgkmcnt(0)
	v_mfma_f32_32x32x16_bf16 v[80:95], v[124:127], v[120:123], v[80:95]
	v_add_u32_e32 v124, s4, v201
	v_mfma_f32_32x32x16_bf16 v[64:79], v[128:131], v[120:123], v[64:79]
	ds_read_b128 v[120:123], v124 offset:49152
	ds_read_b128 v[124:127], v124 offset:61440
	s_waitcnt lgkmcnt(0)
	v_mfma_f32_32x32x16_bf16 v[80:95], v[120:123], v[116:119], v[80:95]
	v_add_u32_e32 v120, s4, v198
	v_mfma_f32_32x32x16_bf16 v[64:79], v[124:127], v[116:119], v[64:79]
	ds_read_b128 v[116:119], v120 offset:49152
	ds_read_b128 v[120:123], v120 offset:61440
	s_waitcnt lgkmcnt(0)
	v_mfma_f32_32x32x16_bf16 v[80:95], v[116:119], v[112:115], v[80:95]
	v_add_u32_e32 v116, s4, v197
	v_mfma_f32_32x32x16_bf16 v[64:79], v[120:123], v[112:115], v[64:79]
	ds_read_b128 v[112:115], v116 offset:49152
	ds_read_b128 v[116:119], v116 offset:61440
	v_exp_f32_e32 v120, v144
	v_exp_f32_e32 v121, v145
	s_waitcnt lgkmcnt(0)
	v_mfma_f32_32x32x16_bf16 v[80:95], v[112:115], v[108:111], v[80:95]
	v_add_u32_e32 v112, s4, v196
	v_mfma_f32_32x32x16_bf16 v[64:79], v[116:119], v[108:111], v[64:79]
	ds_read_b128 v[108:111], v112 offset:49152
	ds_read_b128 v[112:115], v112 offset:61440
	v_exp_f32_e32 v116, v148
	v_exp_f32_e32 v117, v149
	v_exp_f32_e32 v118, v146
	v_exp_f32_e32 v119, v147
	s_waitcnt lgkmcnt(0)
	v_mfma_f32_32x32x16_bf16 v[80:95], v[108:111], v[104:107], v[80:95]
	v_add_u32_e32 v108, s4, v195
	v_mfma_f32_32x32x16_bf16 v[64:79], v[112:115], v[104:107], v[64:79]
	ds_read_b128 v[104:107], v108 offset:49152
	ds_read_b128 v[108:111], v108 offset:61440
	v_exp_f32_e32 v114, v150
	v_exp_f32_e32 v115, v151
	s_waitcnt lgkmcnt(0)
	v_mfma_f32_32x32x16_bf16 v[80:95], v[104:107], v[100:103], v[80:95]
	v_add_u32_e32 v104, s4, v194
	v_mfma_f32_32x32x16_bf16 v[64:79], v[108:111], v[100:103], v[64:79]
	ds_read_b128 v[100:103], v104 offset:49152
	ds_read_b128 v[104:107], v104 offset:61440
	v_exp_f32_e32 v108, v154
	v_exp_f32_e32 v109, v155
	v_exp_f32_e32 v110, v152
	v_exp_f32_e32 v111, v153
	s_waitcnt lgkmcnt(0)
	v_mfma_f32_32x32x16_bf16 v[80:95], v[100:103], v[96:99], v[80:95]
	v_cvt_pk_bf16_f32 v100, v211, v212
	v_cvt_pk_bf16_f32 v101, v213, v215
	v_cvt_pk_bf16_f32 v102, v214, v216
	v_cvt_pk_bf16_f32 v103, v217, v219
	s_nop 0
	v_mfma_f32_32x32x16_bf16 v[64:79], v[104:107], v[96:99], v[64:79]
	v_add_f32_e32 v96, 0, v218
	v_add_f32_e32 v96, v220, v96
	v_add_f32_e32 v96, v221, v96
	v_add_f32_e32 v96, v222, v96
	v_add_f32_e32 v96, v223, v96
	v_add_f32_e32 v96, v225, v96
	v_add_f32_e32 v96, v224, v96
	v_add_f32_e32 v96, v226, v96
	v_add_f32_e32 v96, v211, v96
	v_add_f32_e32 v96, v212, v96
	v_add_f32_e32 v96, v213, v96
	v_add_f32_e32 v96, v215, v96
	v_exp_f32_e32 v104, v158
	v_add_f32_e32 v96, v214, v96
	v_exp_f32_e32 v105, v159
	v_add_f32_e32 v96, v216, v96
	v_exp_f32_e32 v106, v156
	v_add_f32_e32 v96, v217, v96
	v_exp_f32_e32 v107, v157
	v_add_f32_e32 v96, v219, v96
	v_add_f32_e32 v96, v104, v96
	v_add_f32_e32 v96, v105, v96
	v_add_f32_e32 v96, v106, v96
	v_add_f32_e32 v96, v107, v96
	v_add_f32_e32 v96, v108, v96
	v_add_f32_e32 v96, v109, v96
	v_add_f32_e32 v96, v110, v96
	v_add_f32_e32 v96, v111, v96
	v_add_f32_e32 v96, v114, v96
	v_add_f32_e32 v96, v115, v96
	v_add_f32_e32 v96, v116, v96
	v_add_f32_e32 v96, v117, v96
	v_add_f32_e32 v96, v118, v96
	v_add_f32_e32 v96, v119, v96
	v_add_f32_e32 v96, v120, v96
	v_add_f32_e32 v112, v121, v96
	v_mov_b32_e32 v113, v112
	v_cvt_pk_bf16_f32 v96, v218, v220
	v_cvt_pk_bf16_f32 v97, v221, v222
	v_cvt_pk_bf16_f32 v98, v223, v225
	v_cvt_pk_bf16_f32 v99, v224, v226
	v_permlane32_swap_b32_e32 v112, v113
	v_cvt_pk_bf16_f32 v104, v104, v105
	v_cvt_pk_bf16_f32 v105, v106, v107
	v_cvt_pk_bf16_f32 v106, v108, v109
	v_cvt_pk_bf16_f32 v107, v110, v111
	v_cvt_pk_bf16_f32 v108, v114, v115
	v_cvt_pk_bf16_f32 v109, v116, v117
	v_cvt_pk_bf16_f32 v110, v118, v119
	v_cvt_pk_bf16_f32 v111, v120, v121
	v_add_u32_e32 v130, s17, v190
	ds_read_b64_tr_b16 v[114:115], v130
	ds_read_b64_tr_b16 v[116:117], v130 offset:2048
	ds_read_b64_tr_b16 v[118:119], v130 offset:4096
	ds_read_b64_tr_b16 v[120:121], v130 offset:6144
	ds_read_b64_tr_b16 v[122:123], v130 offset:8192
	ds_read_b64_tr_b16 v[124:125], v130 offset:10240
	ds_read_b64_tr_b16 v[126:127], v130 offset:12288
	ds_read_b64_tr_b16 v[128:129], v130 offset:14336
	s_waitcnt lgkmcnt(0)
; #define RESC(a) do { if (__any((a) < 1.f)) { if (hi == 0) al_l[r32] = (a); asm volatile("s_waitcnt lgkmcnt(0)" ::: "memory"); \
;     for (int d = 0; d < 4; ++d) for (int r = 0; r < 16; ++r) o[d][r] *= al_l[crow(r, hi)]; } } while (0)
; __device__ __forceinline__ void partialSM(f32x16& p0, f32x16& p1, float& m_reg, float& mn, float& alpha) {
;   constexpr float C = ASCALE * 1.4426950408889634f;
;   float pmax = p0[0]; for (int r = 1; r < 16; ++r) pmax = fmaxf(pmax, p0[r]); for (int r = 0; r < 16; ++r) pmax = fmaxf(pmax, p1[r]);
;   { auto rr = __builtin_amdgcn_permlane32_swap(__float_as_uint(pmax), __float_as_uint(pmax), false, false);
;     pmax = fmaxf(__uint_as_float(rr[0]), __uint_as_float(rr[1])); }
;   if (__builtin_expect(__all(pmax - m_reg <= THR / ASCALE), 1)) { mn = m_reg; alpha = 1.f; }
;   else { mn = fmaxf(m_reg, pmax); alpha = __builtin_amdgcn_exp2f((m_reg - mn) * C); m_reg = mn; }
; __device__ __forceinline__ void attn_body(const u16* __restrict__ Qb, const u16* __restrict__ Kh, const u16* __restrict__ Vh,
;                                           u16* __restrict__ Ob, int seq, int wvs) {
;     ...
;   pv_d0(o, vb0 + sV * SHM_V, pa0, pa1, pa2, pa3); partialSM(pB0, pB1, m_reg, mnB, alB);
;   RESC(alB);
	v_mfma_f32_32x32x16_bf16 v[0:15], v[96:99], v[114:117], v[0:15]
	v_mfma_f32_32x32x16_bf16 v[0:15], v[100:103], v[118:121], v[0:15]
	v_mfma_f32_32x32x16_bf16 v[0:15], v[104:107], v[122:125], v[0:15]
	v_mfma_f32_32x32x16_bf16 v[0:15], v[108:111], v[126:129], v[0:15]
	ds_read_b64_tr_b16 v[114:115], v130 offset:512
	ds_read_b64_tr_b16 v[116:117], v130 offset:2560
	ds_read_b64_tr_b16 v[118:119], v130 offset:4608
	ds_read_b64_tr_b16 v[120:121], v130 offset:6656
	ds_read_b64_tr_b16 v[122:123], v130 offset:8704
	ds_read_b64_tr_b16 v[124:125], v130 offset:10752
	ds_read_b64_tr_b16 v[126:127], v130 offset:12800
	ds_read_b64_tr_b16 v[128:129], v130 offset:14848
	s_waitcnt lgkmcnt(0)
	v_mfma_f32_32x32x16_bf16 v[48:63], v[96:99], v[114:117], v[48:63]
	v_mfma_f32_32x32x16_bf16 v[48:63], v[100:103], v[118:121], v[48:63]
	v_mfma_f32_32x32x16_bf16 v[48:63], v[104:107], v[122:125], v[48:63]
	v_mfma_f32_32x32x16_bf16 v[48:63], v[108:111], v[126:129], v[48:63]
	ds_read_b64_tr_b16 v[114:115], v130 offset:1024
	ds_read_b64_tr_b16 v[116:117], v130 offset:3072
	ds_read_b64_tr_b16 v[118:119], v130 offset:5120
	ds_read_b64_tr_b16 v[120:121], v130 offset:7168
	ds_read_b64_tr_b16 v[122:123], v130 offset:9216
	ds_read_b64_tr_b16 v[124:125], v130 offset:11264
	ds_read_b64_tr_b16 v[126:127], v130 offset:13312
	ds_read_b64_tr_b16 v[128:129], v130 offset:15360
	s_waitcnt lgkmcnt(0)
	v_mfma_f32_32x32x16_bf16 v[32:47], v[96:99], v[114:117], v[32:47]
	v_mfma_f32_32x32x16_bf16 v[32:47], v[100:103], v[118:121], v[32:47]
	v_mfma_f32_32x32x16_bf16 v[32:47], v[104:107], v[122:125], v[32:47]
	v_mfma_f32_32x32x16_bf16 v[32:47], v[108:111], v[126:129], v[32:47]
	ds_read_b64_tr_b16 v[114:115], v130 offset:1536
	ds_read_b64_tr_b16 v[116:117], v130 offset:3584
	ds_read_b64_tr_b16 v[118:119], v130 offset:5632
	ds_read_b64_tr_b16 v[120:121], v130 offset:7680
	ds_read_b64_tr_b16 v[122:123], v130 offset:9728
	ds_read_b64_tr_b16 v[124:125], v130 offset:11776
	ds_read_b64_tr_b16 v[126:127], v130 offset:13824
	ds_read_b64_tr_b16 v[128:129], v130 offset:15872
	s_waitcnt lgkmcnt(0)
	v_mfma_f32_32x32x16_bf16 v[16:31], v[96:99], v[114:117], v[16:31]
	v_max_f32_e32 v96, v81, v81
	v_max_f32_e32 v97, v80, v80
	v_max_f32_e32 v96, v97, v96
	v_max3_f32 v96, v96, v82, v83
	v_max3_f32 v96, v96, v84, v85
	v_max3_f32 v96, v96, v86, v87
	v_max3_f32 v96, v96, v88, v89
	v_max3_f32 v96, v96, v90, v91
	v_max3_f32 v96, v96, v92, v93
	v_mfma_f32_32x32x16_bf16 v[16:31], v[100:103], v[118:121], v[16:31]
	v_max3_f32 v96, v96, v94, v95
	v_max3_f32 v96, v96, v64, v65
	v_max3_f32 v96, v96, v66, v67
	v_max3_f32 v96, v96, v68, v69
	v_max3_f32 v96, v96, v70, v71
	v_max3_f32 v96, v96, v72, v73
	v_max3_f32 v96, v96, v74, v75
	v_max3_f32 v96, v96, v76, v77
	v_mfma_f32_32x32x16_bf16 v[16:31], v[104:107], v[122:125], v[16:31]
	v_max3_f32 v96, v96, v78, v79
	v_mov_b32_e32 v97, v96
	s_nop 1
	v_permlane32_swap_b32_e32 v96, v97
	v_max_f32_e32 v97, v97, v97
	v_max_f32_e32 v96, v96, v96
	v_max_f32_e32 v96, v96, v97
	v_sub_f32_e32 v97, v96, v191
	v_cmp_ge_f32_e32 vcc, s35, v97
	v_max_f32_e32 v97, v191, v191
	v_max_f32_e32 v97, v97, v96
	v_mfma_f32_32x32x16_bf16 v[16:31], v[108:111], v[126:129], v[16:31]
	v_sub_f32_e32 v96, v191, v97
	v_mul_f32_e32 v96, 0x3dd53b94, v96
	v_exp_f32_e32 v96, v96
	s_cmp_eq_u64 vcc, exec
	s_cselect_b64 s[8:9], -1, 0
	v_cndmask_b32_e64 v96, v96, 1.0, s[8:9]
	v_cmp_gt_f32_e32 vcc, 1.0, v96
	s_cbranch_vccz .LBB0_376
	s_and_saveexec_b64 s[4:5], s[6:7]
	ds_write_b32 v188, v96 offset:128
	s_or_b64 exec, exec, s[4:5]
	s_waitcnt lgkmcnt(0)
	v_add_u32_e32 v110, v165, v160
	ds_read_b128 v[98:101], v110 offset:224
	ds_read_b128 v[102:105], v110 offset:192
	ds_read_b128 v[106:109], v110 offset:160
	ds_read_b128 v[114:117], v110 offset:128
	s_waitcnt lgkmcnt(0)
	v_pk_mul_f32 v[12:13], v[12:13], v[98:99]
	v_pk_mul_f32 v[8:9], v[8:9], v[102:103]
	v_pk_mul_f32 v[4:5], v[4:5], v[106:107]
	v_pk_mul_f32 v[14:15], v[14:15], v[100:101]
	v_pk_mul_f32 v[10:11], v[10:11], v[104:105]
	v_pk_mul_f32 v[6:7], v[6:7], v[108:109]
	v_pk_mul_f32 v[2:3], v[2:3], v[116:117]
	v_pk_mul_f32 v[0:1], v[0:1], v[114:115]
	v_pk_mul_f32 v[60:61], v[60:61], v[98:99]
	v_pk_mul_f32 v[56:57], v[56:57], v[102:103]
	v_pk_mul_f32 v[52:53], v[52:53], v[106:107]
	v_pk_mul_f32 v[62:63], v[62:63], v[100:101]
	v_pk_mul_f32 v[58:59], v[58:59], v[104:105]
	v_pk_mul_f32 v[54:55], v[54:55], v[108:109]
	v_pk_mul_f32 v[50:51], v[50:51], v[116:117]
	v_pk_mul_f32 v[48:49], v[48:49], v[114:115]
	v_pk_mul_f32 v[44:45], v[44:45], v[98:99]
	v_pk_mul_f32 v[40:41], v[40:41], v[102:103]
	v_pk_mul_f32 v[36:37], v[36:37], v[106:107]
	v_pk_mul_f32 v[46:47], v[46:47], v[100:101]
	v_pk_mul_f32 v[42:43], v[42:43], v[104:105]
	v_pk_mul_f32 v[38:39], v[38:39], v[108:109]
	v_pk_mul_f32 v[34:35], v[34:35], v[116:117]
	v_pk_mul_f32 v[32:33], v[32:33], v[114:115]
	v_pk_mul_f32 v[28:29], v[28:29], v[98:99]
	v_pk_mul_f32 v[24:25], v[24:25], v[102:103]
	v_pk_mul_f32 v[20:21], v[20:21], v[106:107]
	v_pk_mul_f32 v[30:31], v[30:31], v[100:101]
	v_pk_mul_f32 v[26:27], v[26:27], v[104:105]
	v_pk_mul_f32 v[22:23], v[22:23], v[108:109]
	v_pk_mul_f32 v[18:19], v[18:19], v[116:117]
	v_pk_mul_f32 v[16:17], v[16:17], v[114:115]
; #define SBAR() __builtin_amdgcn_sched_barrier(0)
; #define TBAR(n) do { asm volatile("s_waitcnt vmcnt(" #n ") lgkmcnt(0)" ::: "memory"); __builtin_amdgcn_s_barrier(); SBAR(); } while (0)
; __device__ __forceinline__ void finishSM(f32x16& p0, f32x16& p1, float alpha, float& l_reg, bf16x8& pa0, bf16x8& pa1, bf16x8& pa2, bf16x8& pa3) {
;   for (int r = 0; r < 16; ++r) p1[r] = __builtin_amdgcn_exp2f(p1[r]);
;   float ps = 0; for (int r = 0; r < 16; ++r) ps += p0[r]; for (int r = 0; r < 16; ++r) ps += p1[r];
;   { auto rr = __builtin_amdgcn_permlane32_swap(__float_as_uint(ps), __float_as_uint(ps), false, false);
;     ps = __uint_as_float(rr[0]) + __uint_as_float(rr[1]); }
;   l_reg = l_reg * alpha + ps;
;     ...
;   PK4(p0, 0, pa0); PK4(p0, 8, pa1); PK4(p1, 0, pa2); PK4(p1, 8, pa3);
; __device__ __forceinline__ void attn_body(const u16* __restrict__ Qb, const u16* __restrict__ Kh, const u16* __restrict__ Vh,
;                                           u16* __restrict__ Ob, int seq, int wvs) {
;     ...
;   TBAR(0);
;   finishSM(pB0, pB1, alB, l_reg, pa0, pa1, pa2, pa3); SBAR();
;   pv_d0(o, vb0 + sV * SHM_V, pa0, pa1, pa2, pa3);
.LBB0_376:
	v_cndmask_b32_e64 v97, v97, v191, s[8:9]
	s_waitcnt vmcnt(0) lgkmcnt(0)
	v_mul_f32_e32 v97, 0xbdd53b94, v97
	v_fmamk_f32 v80, v80, 0x3dd53b94, v97
	v_fmamk_f32 v81, v81, 0x3dd53b94, v97
	v_fmamk_f32 v82, v82, 0x3dd53b94, v97
	v_fmamk_f32 v83, v83, 0x3dd53b94, v97
	v_fmamk_f32 v84, v84, 0x3dd53b94, v97
	v_fmamk_f32 v85, v85, 0x3dd53b94, v97
	v_fmamk_f32 v86, v86, 0x3dd53b94, v97
	v_fmamk_f32 v87, v87, 0x3dd53b94, v97
	v_fmamk_f32 v88, v88, 0x3dd53b94, v97
	v_fmamk_f32 v89, v89, 0x3dd53b94, v97
	v_fmamk_f32 v90, v90, 0x3dd53b94, v97
	v_fmamk_f32 v91, v91, 0x3dd53b94, v97
	v_fmamk_f32 v92, v92, 0x3dd53b94, v97
	v_fmamk_f32 v93, v93, 0x3dd53b94, v97
	v_fmamk_f32 v94, v94, 0x3dd53b94, v97
	v_fmamk_f32 v95, v95, 0x3dd53b94, v97
	v_fmamk_f32 v64, v64, 0x3dd53b94, v97
	v_fmamk_f32 v65, v65, 0x3dd53b94, v97
	v_fmamk_f32 v66, v66, 0x3dd53b94, v97
	v_fmamk_f32 v67, v67, 0x3dd53b94, v97
	v_fmamk_f32 v68, v68, 0x3dd53b94, v97
	v_fmamk_f32 v69, v69, 0x3dd53b94, v97
	v_fmamk_f32 v70, v70, 0x3dd53b94, v97
	v_fmamk_f32 v71, v71, 0x3dd53b94, v97
	v_fmamk_f32 v72, v72, 0x3dd53b94, v97
	v_fmamk_f32 v73, v73, 0x3dd53b94, v97
	v_fmamk_f32 v74, v74, 0x3dd53b94, v97
	v_fmamk_f32 v75, v75, 0x3dd53b94, v97
	v_fmamk_f32 v76, v76, 0x3dd53b94, v97
	v_fmamk_f32 v77, v77, 0x3dd53b94, v97
	v_fmamk_f32 v78, v78, 0x3dd53b94, v97
	v_fmac_f32_e32 v97, 0x3dd53b94, v79
	v_exp_f32_e32 v79, v80
	v_exp_f32_e32 v98, v81
	v_exp_f32_e32 v82, v82
	v_exp_f32_e32 v83, v83
	v_exp_f32_e32 v84, v84
	v_exp_f32_e32 v85, v85
	v_exp_f32_e32 v86, v86
	v_exp_f32_e32 v87, v87
	v_exp_f32_e32 v88, v88
	v_exp_f32_e32 v89, v89
	v_exp_f32_e32 v90, v90
	v_exp_f32_e32 v91, v91
	v_exp_f32_e32 v92, v92
	v_exp_f32_e32 v93, v93
	v_exp_f32_e32 v94, v94
	v_exp_f32_e32 v95, v95
	s_barrier
	v_exp_f32_e32 v99, v68
	v_add_f32_e32 v68, 0, v79
	v_add_f32_e32 v68, v98, v68
	v_add_f32_e32 v68, v82, v68
	v_add_f32_e32 v68, v83, v68
	v_add_f32_e32 v68, v84, v68
	v_add_f32_e32 v68, v85, v68
	v_add_f32_e32 v68, v86, v68
	v_add_f32_e32 v68, v87, v68
	v_add_f32_e32 v68, v88, v68
	v_add_f32_e32 v68, v89, v68
	v_add_f32_e32 v68, v90, v68
	v_add_f32_e32 v68, v91, v68
	v_exp_f32_e32 v64, v64
	v_add_f32_e32 v68, v92, v68
	v_exp_f32_e32 v65, v65
	v_add_f32_e32 v68, v93, v68
	v_exp_f32_e32 v66, v66
	v_add_f32_e32 v68, v94, v68
	v_exp_f32_e32 v67, v67
	v_add_f32_e32 v68, v95, v68
	v_add_f32_e32 v68, v64, v68
	v_exp_f32_e32 v100, v69
	v_add_f32_e32 v68, v65, v68
	v_exp_f32_e32 v101, v70
	v_add_f32_e32 v68, v66, v68
	v_exp_f32_e32 v71, v71
	v_add_f32_e32 v68, v67, v68
	v_exp_f32_e32 v102, v72
	v_add_f32_e32 v68, v99, v68
	v_exp_f32_e32 v103, v73
	v_add_f32_e32 v68, v100, v68
	v_exp_f32_e32 v104, v74
	v_add_f32_e32 v68, v101, v68
	v_exp_f32_e32 v105, v75
	v_add_f32_e32 v68, v71, v68
	v_exp_f32_e32 v106, v76
	v_add_f32_e32 v68, v102, v68
	v_exp_f32_e32 v107, v77
	v_add_f32_e32 v68, v103, v68
	v_exp_f32_e32 v108, v78
	v_add_f32_e32 v68, v104, v68
	v_exp_f32_e32 v97, v97
	v_add_f32_e32 v68, v105, v68
	v_add_f32_e32 v68, v106, v68
	v_add_f32_e32 v68, v107, v68
	v_add_f32_e32 v68, v108, v68
	v_add_f32_e32 v80, v97, v68
	v_mov_b32_e32 v81, v80
	s_nop 1
	v_permlane32_swap_b32_e32 v80, v81
	v_cvt_pk_bf16_f32 v76, v79, v98
	v_cvt_pk_bf16_f32 v77, v82, v83
	v_cvt_pk_bf16_f32 v78, v84, v85
	v_cvt_pk_bf16_f32 v79, v86, v87
	v_cvt_pk_bf16_f32 v72, v88, v89
	v_cvt_pk_bf16_f32 v73, v90, v91
	v_cvt_pk_bf16_f32 v74, v92, v93
	v_cvt_pk_bf16_f32 v75, v94, v95
	v_cvt_pk_bf16_f32 v68, v64, v65
	v_cvt_pk_bf16_f32 v69, v66, v67
	v_cvt_pk_bf16_f32 v70, v99, v100
	v_cvt_pk_bf16_f32 v71, v101, v71
	v_cvt_pk_bf16_f32 v64, v102, v103
	v_cvt_pk_bf16_f32 v65, v104, v105
	v_cvt_pk_bf16_f32 v66, v106, v107
	v_cvt_pk_bf16_f32 v67, v108, v97
	v_add_u32_e32 v86, s16, v190
	ds_read_b64_tr_b16 v[82:83], v86
	ds_read_b64_tr_b16 v[84:85], v86 offset:2048
	s_waitcnt lgkmcnt(0)
	v_mfma_f32_32x32x16_bf16 v[0:15], v[76:79], v[82:85], v[0:15]
	ds_read_b64_tr_b16 v[82:83], v86 offset:4096
	ds_read_b64_tr_b16 v[84:85], v86 offset:6144
	s_waitcnt lgkmcnt(0)
	v_mfma_f32_32x32x16_bf16 v[0:15], v[72:75], v[82:85], v[0:15]
	ds_read_b64_tr_b16 v[82:83], v86 offset:8192
	ds_read_b64_tr_b16 v[84:85], v86 offset:10240
	s_waitcnt lgkmcnt(0)
	v_mfma_f32_32x32x16_bf16 v[0:15], v[68:71], v[82:85], v[0:15]
	ds_read_b64_tr_b16 v[82:83], v86 offset:12288
	ds_read_b64_tr_b16 v[84:85], v86 offset:14336
	s_waitcnt lgkmcnt(0)
	v_mfma_f32_32x32x16_bf16 v[0:15], v[64:67], v[82:85], v[0:15]
	ds_read_b64_tr_b16 v[82:83], v86 offset:512
	ds_read_b64_tr_b16 v[84:85], v86 offset:2560
	s_waitcnt lgkmcnt(0)
	v_mfma_f32_32x32x16_bf16 v[48:63], v[76:79], v[82:85], v[48:63]
	ds_read_b64_tr_b16 v[82:83], v86 offset:4608
	ds_read_b64_tr_b16 v[84:85], v86 offset:6656
	s_waitcnt lgkmcnt(0)
	v_mfma_f32_32x32x16_bf16 v[48:63], v[72:75], v[82:85], v[48:63]
	ds_read_b64_tr_b16 v[82:83], v86 offset:8704
	ds_read_b64_tr_b16 v[84:85], v86 offset:10752
	s_waitcnt lgkmcnt(0)
	v_mfma_f32_32x32x16_bf16 v[48:63], v[68:71], v[82:85], v[48:63]
	ds_read_b64_tr_b16 v[82:83], v86 offset:12800
	ds_read_b64_tr_b16 v[84:85], v86 offset:14848
	s_waitcnt lgkmcnt(0)
	v_mfma_f32_32x32x16_bf16 v[48:63], v[64:67], v[82:85], v[48:63]
	ds_read_b64_tr_b16 v[82:83], v86 offset:1024
	ds_read_b64_tr_b16 v[84:85], v86 offset:3072
	s_waitcnt lgkmcnt(0)
	v_mfma_f32_32x32x16_bf16 v[32:47], v[76:79], v[82:85], v[32:47]
	ds_read_b64_tr_b16 v[82:83], v86 offset:5120
	ds_read_b64_tr_b16 v[84:85], v86 offset:7168
	s_waitcnt lgkmcnt(0)
	v_mfma_f32_32x32x16_bf16 v[32:47], v[72:75], v[82:85], v[32:47]
	ds_read_b64_tr_b16 v[82:83], v86 offset:9216
	ds_read_b64_tr_b16 v[84:85], v86 offset:11264
	s_waitcnt lgkmcnt(0)
; __device__ __forceinline__ u16 f2bf(float x) { return (u16)(cvtpk(x, 0.f) & 0xffffu); }
; __device__ __forceinline__ int crow(int r, int hi) { return (r & 3) + 8 * (r >> 2) + 4 * hi; }
; __device__ __forceinline__ void attn_body(const u16* __restrict__ Qb, const u16* __restrict__ Kh, const u16* __restrict__ Vh,
;                                           u16* __restrict__ Ob, int seq, int wvs) {
;     ...
;   pv_d0(o, vb0 + sV * SHM_V, pa0, pa1, pa2, pa3);
;   if (hi == 0) li_l[r32] = l_reg; asm volatile("s_waitcnt lgkmcnt(0)" ::: "memory");
;   float rli[16];
; #pragma unroll
;   for (int r = 0; r < 16; ++r) rli[r] = __builtin_amdgcn_rcpf(li_l[crow(r, hi)]);
;   u16* Ow = Ob + (long)(wid * QBLK) * DM;
; #pragma unroll
;   for (int r = 0; r < 16; ++r) { int orow = crow(r, hi);
; #pragma unroll
;     for (int d0 = 0; d0 < 4; ++d0) Ow[(long)orow * DM + d0 * 32 + r32] = f2bf(o[d0][r] * rli[r]); }
	v_mfma_f32_32x32x16_bf16 v[32:47], v[68:71], v[82:85], v[32:47]
	ds_read_b64_tr_b16 v[82:83], v86 offset:13312
	ds_read_b64_tr_b16 v[84:85], v86 offset:15360
	s_waitcnt lgkmcnt(0)
	v_mfma_f32_32x32x16_bf16 v[32:47], v[64:67], v[82:85], v[32:47]
	ds_read_b64_tr_b16 v[82:83], v86 offset:1536
	ds_read_b64_tr_b16 v[84:85], v86 offset:3584
	s_waitcnt lgkmcnt(0)
	v_mfma_f32_32x32x16_bf16 v[16:31], v[76:79], v[82:85], v[16:31]
	ds_read_b64_tr_b16 v[76:77], v86 offset:5632
	ds_read_b64_tr_b16 v[78:79], v86 offset:7680
	s_waitcnt lgkmcnt(0)
	v_mfma_f32_32x32x16_bf16 v[16:31], v[72:75], v[76:79], v[16:31]
	ds_read_b64_tr_b16 v[72:73], v86 offset:9728
	ds_read_b64_tr_b16 v[74:75], v86 offset:11776
	s_waitcnt lgkmcnt(0)
	v_mfma_f32_32x32x16_bf16 v[16:31], v[68:71], v[72:75], v[16:31]
	ds_read_b64_tr_b16 v[68:69], v86 offset:13824
	ds_read_b64_tr_b16 v[70:71], v86 offset:15872
	s_waitcnt lgkmcnt(0)
	v_mfma_f32_32x32x16_bf16 v[16:31], v[64:67], v[68:71], v[16:31]
	s_and_saveexec_b64 s[4:5], s[6:7]
	v_add_f32_e32 v64, v112, v113
	v_fmac_f32_e32 v64, v189, v176
	v_add_f32_e32 v65, v80, v81
	v_fmac_f32_e32 v65, v64, v96
	ds_write_b32 v188, v65
	s_or_b64 exec, exec, s[4:5]
	s_waitcnt lgkmcnt(0)
	v_add_u32_e32 v72, v165, v160
	ds_read_b128 v[64:67], v72
	ds_read_b128 v[68:71], v72 offset:32
	v_ashrrev_i32_e32 v165, 31, v164
	v_readlane_b32 s4, v254, 43
	v_readlane_b32 s5, v254, 44
	s_waitcnt lgkmcnt(0)
	v_rcp_f32_e32 v73, v64
	v_rcp_f32_e32 v74, v65
	v_rcp_f32_e32 v75, v66
	v_rcp_f32_e32 v76, v67
	ds_read_b128 v[64:67], v72 offset:64
	v_rcp_f32_e32 v77, v68
	v_rcp_f32_e32 v78, v69
	v_rcp_f32_e32 v79, v70
	v_rcp_f32_e32 v80, v71
	ds_read_b128 v[68:71], v72 offset:96
	s_waitcnt lgkmcnt(0)
	v_rcp_f32_e32 v72, v64
	v_rcp_f32_e32 v81, v65
	v_lshlrev_b64 v[64:65], 12, v[164:165]
	v_lshl_add_u64 v[64:65], s[4:5], 0, v[64:65]
	v_lshlrev_b32_e32 v160, 1, v187
	v_rcp_f32_e32 v82, v66
	v_rcp_f32_e32 v83, v67
	v_lshlrev_b32_e32 v66, 14, v186
	v_lshl_add_u64 v[64:65], v[64:65], 0, v[160:161]
	v_mov_b32_e32 v67, v161
	v_mul_f32_e32 v0, v0, v73
	v_lshl_add_u64 v[64:65], v[64:65], 0, v[66:67]
	v_cvt_pk_bf16_f32 v0, v0, s0
	flat_store_short v[64:65], v0
	v_mul_f32_e32 v0, v48, v73
	v_cvt_pk_bf16_f32 v0, v0, s0
	flat_store_short v[64:65], v0 offset:64
	v_mul_f32_e32 v0, v32, v73
	v_cvt_pk_bf16_f32 v0, v0, s0
	flat_store_short v[64:65], v0 offset:128
	v_mul_f32_e32 v0, v16, v73
	v_cvt_pk_bf16_f32 v0, v0, s0
	flat_store_short v[64:65], v0 offset:192
	v_mul_f32_e32 v0, v1, v74
	s_movk_i32 s4, 0x1000
	v_cvt_pk_bf16_f32 v16, v0, s0
	v_add_co_u32_e32 v0, vcc, s4, v64
	s_movk_i32 s4, 0x2000
	s_nop 0
	v_addc_co_u32_e32 v1, vcc, 0, v65, vcc
	flat_store_short v[0:1], v16
	v_mul_f32_e32 v16, v49, v74
	v_cvt_pk_bf16_f32 v16, v16, s0
	flat_store_short v[0:1], v16 offset:64
	v_mul_f32_e32 v16, v33, v74
	v_cvt_pk_bf16_f32 v16, v16, s0
	flat_store_short v[0:1], v16 offset:128
	v_mul_f32_e32 v16, v17, v74
	v_cvt_pk_bf16_f32 v16, v16, s0
	flat_store_short v[0:1], v16 offset:192
	v_mul_f32_e32 v0, v2, v75
	v_cvt_pk_bf16_f32 v2, v0, s0
	v_add_co_u32_e32 v0, vcc, s4, v64
	s_movk_i32 s4, 0x3000
	s_nop 0
	v_addc_co_u32_e32 v1, vcc, 0, v65, vcc
	flat_store_short v[0:1], v2
	v_mul_f32_e32 v2, v50, v75
	v_cvt_pk_bf16_f32 v2, v2, s0
	flat_store_short v[0:1], v2 offset:64
	v_mul_f32_e32 v2, v34, v75
	v_cvt_pk_bf16_f32 v2, v2, s0
	flat_store_short v[0:1], v2 offset:128
	v_mul_f32_e32 v2, v18, v75
	v_cvt_pk_bf16_f32 v2, v2, s0
	flat_store_short v[0:1], v2 offset:192
	v_mul_f32_e32 v0, v3, v76
	v_cvt_pk_bf16_f32 v2, v0, s0
	v_add_co_u32_e32 v0, vcc, s4, v64
	s_mov_b32 s4, 0x8000
	s_nop 0
	v_addc_co_u32_e32 v1, vcc, 0, v65, vcc
	flat_store_short v[0:1], v2
	v_mul_f32_e32 v2, v51, v76
	v_cvt_pk_bf16_f32 v2, v2, s0
	flat_store_short v[0:1], v2 offset:64
	v_mul_f32_e32 v2, v35, v76
	v_cvt_pk_bf16_f32 v2, v2, s0
	flat_store_short v[0:1], v2 offset:128
	v_mul_f32_e32 v2, v19, v76
	v_cvt_pk_bf16_f32 v2, v2, s0
	flat_store_short v[0:1], v2 offset:192
	v_mul_f32_e32 v0, v4, v77
	v_cvt_pk_bf16_f32 v2, v0, s0
	v_add_co_u32_e32 v0, vcc, s4, v64
	s_mov_b32 s4, 0x9000
	s_nop 0
	v_addc_co_u32_e32 v1, vcc, 0, v65, vcc
	flat_store_short v[0:1], v2
	v_mul_f32_e32 v2, v52, v77
	v_cvt_pk_bf16_f32 v2, v2, s0
	flat_store_short v[0:1], v2 offset:64
	v_mul_f32_e32 v2, v36, v77
	v_cvt_pk_bf16_f32 v2, v2, s0
	flat_store_short v[0:1], v2 offset:128
	v_mul_f32_e32 v2, v20, v77
	v_cvt_pk_bf16_f32 v2, v2, s0
	flat_store_short v[0:1], v2 offset:192
	v_mul_f32_e32 v0, v5, v78
	v_cvt_pk_bf16_f32 v2, v0, s0
	v_add_co_u32_e32 v0, vcc, s4, v64
	s_mov_b32 s4, 0xa000
	s_nop 0
	v_addc_co_u32_e32 v1, vcc, 0, v65, vcc
	flat_store_short v[0:1], v2
	v_mul_f32_e32 v2, v53, v78
	v_cvt_pk_bf16_f32 v2, v2, s0
	flat_store_short v[0:1], v2 offset:64
	v_mul_f32_e32 v2, v37, v78
	v_cvt_pk_bf16_f32 v2, v2, s0
	flat_store_short v[0:1], v2 offset:128
	v_mul_f32_e32 v2, v21, v78
	v_cvt_pk_bf16_f32 v2, v2, s0
	flat_store_short v[0:1], v2 offset:192
	v_mul_f32_e32 v0, v6, v79
	v_cvt_pk_bf16_f32 v2, v0, s0
; __device__ __forceinline__ u16 f2bf(float x) { return (u16)(cvtpk(x, 0.f) & 0xffffu); }
; __device__ __forceinline__ int crow(int r, int hi) { return (r & 3) + 8 * (r >> 2) + 4 * hi; }
; __device__ __forceinline__ void attn_body(const u16* __restrict__ Qb, const u16* __restrict__ Kh, const u16* __restrict__ Vh,
;                                           u16* __restrict__ Ob, int seq, int wvs) {
;     ...
;   u16* Ow = Ob + (long)(wid * QBLK) * DM;
; #pragma unroll
;   for (int r = 0; r < 16; ++r) { int orow = crow(r, hi);
; #pragma unroll
;     for (int d0 = 0; d0 < 4; ++d0) Ow[(long)orow * DM + d0 * 32 + r32] = f2bf(o[d0][r] * rli[r]); }
	v_add_co_u32_e32 v0, vcc, s4, v64
	s_mov_b32 s4, 0xb000
	s_nop 0
	v_addc_co_u32_e32 v1, vcc, 0, v65, vcc
	flat_store_short v[0:1], v2
	v_mul_f32_e32 v2, v54, v79
	v_cvt_pk_bf16_f32 v2, v2, s0
	flat_store_short v[0:1], v2 offset:64
	v_mul_f32_e32 v2, v38, v79
	v_cvt_pk_bf16_f32 v2, v2, s0
	flat_store_short v[0:1], v2 offset:128
	v_mul_f32_e32 v2, v22, v79
	v_cvt_pk_bf16_f32 v2, v2, s0
	flat_store_short v[0:1], v2 offset:192
	v_mul_f32_e32 v0, v7, v80
	v_cvt_pk_bf16_f32 v2, v0, s0
	v_add_co_u32_e32 v0, vcc, s4, v64
	s_mov_b32 s4, 0x10000
	s_nop 0
	v_addc_co_u32_e32 v1, vcc, 0, v65, vcc
	flat_store_short v[0:1], v2
	v_mul_f32_e32 v2, v55, v80
	v_cvt_pk_bf16_f32 v2, v2, s0
	flat_store_short v[0:1], v2 offset:64
	v_mul_f32_e32 v2, v39, v80
	v_cvt_pk_bf16_f32 v2, v2, s0
	flat_store_short v[0:1], v2 offset:128
	v_mul_f32_e32 v2, v23, v80
	v_cvt_pk_bf16_f32 v2, v2, s0
	flat_store_short v[0:1], v2 offset:192
	v_mul_f32_e32 v0, v8, v72
	v_cvt_pk_bf16_f32 v2, v0, s0
	v_add_co_u32_e32 v0, vcc, s4, v64
	s_mov_b32 s4, 0x11000
	s_nop 0
	v_addc_co_u32_e32 v1, vcc, 0, v65, vcc
	flat_store_short v[0:1], v2
	v_mul_f32_e32 v2, v56, v72
	v_cvt_pk_bf16_f32 v2, v2, s0
	flat_store_short v[0:1], v2 offset:64
	v_mul_f32_e32 v2, v40, v72
	v_cvt_pk_bf16_f32 v2, v2, s0
	flat_store_short v[0:1], v2 offset:128
	v_mul_f32_e32 v2, v24, v72
	v_cvt_pk_bf16_f32 v2, v2, s0
	flat_store_short v[0:1], v2 offset:192
	v_mul_f32_e32 v0, v9, v81
	v_cvt_pk_bf16_f32 v2, v0, s0
	v_add_co_u32_e32 v0, vcc, s4, v64
	s_mov_b32 s4, 0x12000
	s_nop 0
	v_addc_co_u32_e32 v1, vcc, 0, v65, vcc
	flat_store_short v[0:1], v2
	v_mul_f32_e32 v2, v57, v81
	v_cvt_pk_bf16_f32 v2, v2, s0
	flat_store_short v[0:1], v2 offset:64
	v_mul_f32_e32 v2, v41, v81
	v_cvt_pk_bf16_f32 v2, v2, s0
	flat_store_short v[0:1], v2 offset:128
	v_mul_f32_e32 v2, v25, v81
	v_cvt_pk_bf16_f32 v2, v2, s0
	flat_store_short v[0:1], v2 offset:192
	v_mul_f32_e32 v0, v10, v82
	v_cvt_pk_bf16_f32 v2, v0, s0
	v_add_co_u32_e32 v0, vcc, s4, v64
	s_mov_b32 s4, 0x13000
	s_nop 0
	v_addc_co_u32_e32 v1, vcc, 0, v65, vcc
	flat_store_short v[0:1], v2
	v_mul_f32_e32 v2, v58, v82
	v_cvt_pk_bf16_f32 v2, v2, s0
	flat_store_short v[0:1], v2 offset:64
	v_mul_f32_e32 v2, v42, v82
	v_cvt_pk_bf16_f32 v2, v2, s0
	flat_store_short v[0:1], v2 offset:128
	v_mul_f32_e32 v2, v26, v82
	v_cvt_pk_bf16_f32 v2, v2, s0
	flat_store_short v[0:1], v2 offset:192
	v_mul_f32_e32 v0, v11, v83
	v_cvt_pk_bf16_f32 v2, v0, s0
	v_add_co_u32_e32 v0, vcc, s4, v64
	v_rcp_f32_e32 v68, v68
	s_nop 0
	v_addc_co_u32_e32 v1, vcc, 0, v65, vcc
	flat_store_short v[0:1], v2
	v_mul_f32_e32 v2, v59, v83
	v_cvt_pk_bf16_f32 v2, v2, s0
	flat_store_short v[0:1], v2 offset:64
	v_mul_f32_e32 v2, v43, v83
	v_cvt_pk_bf16_f32 v2, v2, s0
	flat_store_short v[0:1], v2 offset:128
	v_mul_f32_e32 v2, v27, v83
	v_cvt_pk_bf16_f32 v2, v2, s0
	flat_store_short v[0:1], v2 offset:192
	v_mul_f32_e32 v0, v12, v68
	s_mov_b32 s4, 0x18000
	v_cvt_pk_bf16_f32 v2, v0, s0
	v_add_co_u32_e32 v0, vcc, s4, v64
	v_rcp_f32_e32 v69, v69
	s_nop 0
	v_addc_co_u32_e32 v1, vcc, 0, v65, vcc
	flat_store_short v[0:1], v2
	v_mul_f32_e32 v2, v60, v68
	v_cvt_pk_bf16_f32 v2, v2, s0
	flat_store_short v[0:1], v2 offset:64
	v_mul_f32_e32 v2, v44, v68
	v_cvt_pk_bf16_f32 v2, v2, s0
	flat_store_short v[0:1], v2 offset:128
	v_mul_f32_e32 v2, v28, v68
	v_cvt_pk_bf16_f32 v2, v2, s0
	flat_store_short v[0:1], v2 offset:192
	v_mul_f32_e32 v0, v13, v69
	s_mov_b32 s4, 0x19000
	v_cvt_pk_bf16_f32 v2, v0, s0
	v_add_co_u32_e32 v0, vcc, s4, v64
	v_rcp_f32_e32 v70, v70
	s_nop 0
	v_addc_co_u32_e32 v1, vcc, 0, v65, vcc
	flat_store_short v[0:1], v2
	v_mul_f32_e32 v2, v61, v69
	v_cvt_pk_bf16_f32 v2, v2, s0
	flat_store_short v[0:1], v2 offset:64
	v_mul_f32_e32 v2, v45, v69
	v_cvt_pk_bf16_f32 v2, v2, s0
	flat_store_short v[0:1], v2 offset:128
	v_mul_f32_e32 v2, v29, v69
	v_cvt_pk_bf16_f32 v2, v2, s0
	flat_store_short v[0:1], v2 offset:192
	v_mul_f32_e32 v0, v14, v70
	s_mov_b32 s4, 0x1a000
	v_cvt_pk_bf16_f32 v2, v0, s0
	v_add_co_u32_e32 v0, vcc, s4, v64
	v_rcp_f32_e32 v71, v71
	s_nop 0
	v_addc_co_u32_e32 v1, vcc, 0, v65, vcc
	flat_store_short v[0:1], v2
	v_mul_f32_e32 v2, v62, v70
	v_cvt_pk_bf16_f32 v2, v2, s0
	flat_store_short v[0:1], v2 offset:64
	v_mul_f32_e32 v2, v46, v70
	v_cvt_pk_bf16_f32 v2, v2, s0
	flat_store_short v[0:1], v2 offset:128
	v_mul_f32_e32 v2, v30, v70
	v_cvt_pk_bf16_f32 v2, v2, s0
	flat_store_short v[0:1], v2 offset:192
	v_mul_f32_e32 v0, v15, v71
	s_mov_b32 s4, 0x1b000
	v_cvt_pk_bf16_f32 v2, v0, s0
	v_add_co_u32_e32 v0, vcc, s4, v64
	s_add_i32 s23, s41, 1
	s_nop 0
	v_addc_co_u32_e32 v1, vcc, 0, v65, vcc
	flat_store_short v[0:1], v2
	v_mul_f32_e32 v2, v63, v71
	v_cvt_pk_bf16_f32 v2, v2, s0
	flat_store_short v[0:1], v2 offset:64
	v_mul_f32_e32 v2, v47, v71
	v_cvt_pk_bf16_f32 v2, v2, s0
	flat_store_short v[0:1], v2 offset:128
	v_mul_f32_e32 v2, v31, v71
	v_cvt_pk_bf16_f32 v2, v2, s0
	s_mov_b64 s[24:25], 0
	flat_store_short v[0:1], v2 offset:192
	s_cmp_eq_u32 s23, s92
	s_cbranch_scc0 .LBB0_768
	s_branch .LBB0_245
